# v007 plus: GEMM MFMA segments raise the priority before their opening barrier and drop the repeated lgkmcnt(0) behind it
# speedup vs baseline: 1.0207x; 1.0007x over previous
.LBB0_183:
	s_add_u32 s14, s4, 0xfffc0080
	s_addc_u32 s15, s5, -1
	s_add_i32 s53, 0, 0x10000
	s_cmp_eq_u32 s49, 12
	s_cselect_b32 s55, s21, s15
	s_cselect_b32 s54, s28, s14
	v_add_u32_e32 v142, s53, v147
	s_cselect_b32 s15, s29, s47
	s_cselect_b32 s14, s33, s37
	s_add_i32 s67, 0, 0x14000
	ds_read_b128 v[150:153], v142
	ds_read_b128 v[154:157], v142 offset:1024
	ds_read_b128 v[158:161], v142 offset:2048
	ds_read_b128 v[162:165], v142 offset:3072
	v_add_u32_e32 v142, s67, v147
	ds_read_b128 v[166:169], v142
	ds_read_b128 v[170:173], v142 offset:1024
	ds_read_b128 v[174:177], v142 offset:2048
	ds_read_b128 v[178:181], v142 offset:3072
	v_lshl_add_u64 v[144:145], s[4:5], 0, v[140:141]
	s_add_i32 m0, s59, 0xc000
	ds_read_b128 v[182:185], v149
	ds_read_b128 v[186:189], v149 offset:1024
	ds_read_b128 v[190:193], v149 offset:2048
	ds_read_b128 v[202:205], v149 offset:3072
	ds_read_b128 v[206:209], v149 offset:4096
	ds_read_b128 v[210:213], v149 offset:5120
	ds_read_b128 v[214:217], v149 offset:6144
	ds_read_b128 v[218:221], v149 offset:7168
	global_load_lds_dwordx4 v[144:145], off
	v_lshl_add_u64 v[144:145], s[4:5], 0, v[138:139]
	s_add_i32 m0, s59, 0xe000
	s_nop 0
	global_load_lds_dwordx4 v[144:145], off
	s_waitcnt vmcnt(8)
	s_waitcnt lgkmcnt(0)
	s_setprio 1
	s_barrier
	v_mfma_f32_16x16x32_bf16 v[126:129], v[150:153], v[182:185], v[126:129]
	v_mfma_f32_16x16x32_bf16 v[122:125], v[158:161], v[182:185], v[122:125]
	v_mfma_f32_16x16x32_bf16 v[110:113], v[150:153], v[190:193], v[110:113]
	v_mfma_f32_16x16x32_bf16 v[106:109], v[158:161], v[190:193], v[106:109]
	v_mfma_f32_16x16x32_bf16 v[94:97], v[150:153], v[206:209], v[94:97]
	v_mfma_f32_16x16x32_bf16 v[90:93], v[158:161], v[206:209], v[90:93]
	v_mfma_f32_16x16x32_bf16 v[78:81], v[150:153], v[214:217], v[78:81]
	v_mfma_f32_16x16x32_bf16 v[74:77], v[158:161], v[214:217], v[74:77]
	v_mfma_f32_16x16x32_bf16 v[126:129], v[154:157], v[186:189], v[126:129]
	v_mfma_f32_16x16x32_bf16 v[122:125], v[162:165], v[186:189], v[122:125]
	v_mfma_f32_16x16x32_bf16 v[110:113], v[154:157], v[202:205], v[110:113]
	v_mfma_f32_16x16x32_bf16 v[106:109], v[162:165], v[202:205], v[106:109]
	v_mfma_f32_16x16x32_bf16 v[94:97], v[154:157], v[210:213], v[94:97]
	v_mfma_f32_16x16x32_bf16 v[90:93], v[162:165], v[210:213], v[90:93]
	v_mfma_f32_16x16x32_bf16 v[78:81], v[154:157], v[218:221], v[78:81]
	v_mfma_f32_16x16x32_bf16 v[74:77], v[162:165], v[218:221], v[74:77]
	v_mfma_f32_16x16x32_bf16 v[118:121], v[166:169], v[182:185], v[118:121]
	v_mfma_f32_16x16x32_bf16 v[114:117], v[174:177], v[182:185], v[114:117]
	v_mfma_f32_16x16x32_bf16 v[102:105], v[166:169], v[190:193], v[102:105]
	v_mfma_f32_16x16x32_bf16 v[98:101], v[174:177], v[190:193], v[98:101]
	v_mfma_f32_16x16x32_bf16 v[86:89], v[166:169], v[206:209], v[86:89]
	v_mfma_f32_16x16x32_bf16 v[82:85], v[174:177], v[206:209], v[82:85]
	v_mfma_f32_16x16x32_bf16 v[70:73], v[166:169], v[214:217], v[70:73]
	v_mfma_f32_16x16x32_bf16 v[66:69], v[174:177], v[214:217], v[66:69]
	v_mfma_f32_16x16x32_bf16 v[118:121], v[170:173], v[186:189], v[118:121]
	v_mfma_f32_16x16x32_bf16 v[114:117], v[178:181], v[186:189], v[114:117]
	v_mfma_f32_16x16x32_bf16 v[102:105], v[170:173], v[202:205], v[102:105]
	v_mfma_f32_16x16x32_bf16 v[98:101], v[178:181], v[202:205], v[98:101]
	v_mfma_f32_16x16x32_bf16 v[86:89], v[170:173], v[210:213], v[86:89]
	v_mfma_f32_16x16x32_bf16 v[82:85], v[178:181], v[210:213], v[82:85]
	v_mfma_f32_16x16x32_bf16 v[70:73], v[170:173], v[218:221], v[70:73]
	v_mfma_f32_16x16x32_bf16 v[66:69], v[178:181], v[218:221], v[66:69]
	s_barrier
	s_setprio 0
	s_add_i32 s53, s53, s58
	v_lshl_add_u64 v[144:145], s[14:15], 0, v[134:135]
	s_mov_b32 m0, s53
	ds_read_b128 v[182:185], v149 offset:16384
	ds_read_b128 v[186:189], v149 offset:17408
	ds_read_b128 v[190:193], v149 offset:18432
	ds_read_b128 v[202:205], v149 offset:19456
	ds_read_b128 v[206:209], v149 offset:20480
	ds_read_b128 v[210:213], v149 offset:21504
	ds_read_b128 v[214:217], v149 offset:22528
	ds_read_b128 v[218:221], v149 offset:23552
	global_load_lds_dwordx4 v[144:145], off
	s_add_i32 m0, s53, 0x2000
	s_add_u32 s68, s14, 0x40000
	v_lshl_add_u64 v[222:223], s[14:15], 0, v[130:131]
	s_addc_u32 s69, s15, 0
	s_add_i32 s53, s67, s58
	global_load_lds_dwordx4 v[222:223], off
	v_lshl_add_u64 v[232:233], s[68:69], 0, v[134:135]
	s_mov_b32 m0, s53
	v_lshl_add_u64 v[234:235], s[54:55], 0, v[132:133]
	global_load_lds_dwordx4 v[232:233], off
	v_lshl_add_u64 v[232:233], s[68:69], 0, v[130:131]
	s_add_i32 m0, s53, 0x2000
	s_nop 0
	global_load_lds_dwordx4 v[232:233], off
	v_lshl_add_u64 v[232:233], s[54:55], 0, v[136:137]
	s_mov_b32 m0, s59
	s_nop 0
	global_load_lds_dwordx4 v[232:233], off
	s_mov_b32 m0, s60
	s_nop 0
	global_load_lds_dwordx4 v[234:235], off
	s_waitcnt vmcnt(8)
	s_waitcnt lgkmcnt(0)
	s_setprio 1
	s_barrier
	v_mfma_f32_16x16x32_bf16 v[62:65], v[150:153], v[182:185], v[62:65]
	v_mfma_f32_16x16x32_bf16 v[58:61], v[158:161], v[182:185], v[58:61]
	v_mfma_f32_16x16x32_bf16 v[50:53], v[150:153], v[190:193], v[50:53]
	v_mfma_f32_16x16x32_bf16 v[42:45], v[158:161], v[190:193], v[42:45]
	v_mfma_f32_16x16x32_bf16 v[34:37], v[150:153], v[206:209], v[34:37]
	v_mfma_f32_16x16x32_bf16 v[26:29], v[158:161], v[206:209], v[26:29]
	v_mfma_f32_16x16x32_bf16 v[18:21], v[150:153], v[214:217], v[18:21]
	v_mfma_f32_16x16x32_bf16 v[10:13], v[158:161], v[214:217], v[10:13]
	v_mfma_f32_16x16x32_bf16 v[62:65], v[154:157], v[186:189], v[62:65]
	v_mfma_f32_16x16x32_bf16 v[58:61], v[162:165], v[186:189], v[58:61]
	v_mfma_f32_16x16x32_bf16 v[50:53], v[154:157], v[202:205], v[50:53]
	v_mfma_f32_16x16x32_bf16 v[42:45], v[162:165], v[202:205], v[42:45]
	v_mfma_f32_16x16x32_bf16 v[34:37], v[154:157], v[210:213], v[34:37]
	v_mfma_f32_16x16x32_bf16 v[26:29], v[162:165], v[210:213], v[26:29]
	v_mfma_f32_16x16x32_bf16 v[18:21], v[154:157], v[218:221], v[18:21]
	v_mfma_f32_16x16x32_bf16 v[10:13], v[162:165], v[218:221], v[10:13]
	v_mfma_f32_16x16x32_bf16 v[54:57], v[166:169], v[182:185], v[54:57]
	v_mfma_f32_16x16x32_bf16 v[46:49], v[174:177], v[182:185], v[46:49]
	v_mfma_f32_16x16x32_bf16 v[38:41], v[166:169], v[190:193], v[38:41]
	v_mfma_f32_16x16x32_bf16 v[30:33], v[174:177], v[190:193], v[30:33]
	v_mfma_f32_16x16x32_bf16 v[22:25], v[166:169], v[206:209], v[22:25]
	v_mfma_f32_16x16x32_bf16 v[14:17], v[174:177], v[206:209], v[14:17]
	v_mfma_f32_16x16x32_bf16 v[6:9], v[166:169], v[214:217], v[6:9]
	v_mfma_f32_16x16x32_bf16 v[2:5], v[174:177], v[214:217], v[2:5]
	v_mfma_f32_16x16x32_bf16 v[54:57], v[170:173], v[186:189], v[54:57]
	v_mfma_f32_16x16x32_bf16 v[46:49], v[178:181], v[186:189], v[46:49]
	v_mfma_f32_16x16x32_bf16 v[38:41], v[170:173], v[202:205], v[38:41]
	v_mfma_f32_16x16x32_bf16 v[30:33], v[178:181], v[202:205], v[30:33]
	v_mfma_f32_16x16x32_bf16 v[22:25], v[170:173], v[210:213], v[22:25]
	v_mfma_f32_16x16x32_bf16 v[14:17], v[178:181], v[210:213], v[14:17]
	v_mfma_f32_16x16x32_bf16 v[6:9], v[170:173], v[218:221], v[6:9]
	v_mfma_f32_16x16x32_bf16 v[2:5], v[178:181], v[218:221], v[2:5]
	s_barrier
	s_setprio 0
	s_add_i32 s53, 0, 0x18000
	v_add_u32_e32 v142, s53, v147
	s_add_i32 s67, 0, 0x1c000
	ds_read_b128 v[150:153], v142
	ds_read_b128 v[154:157], v142 offset:1024
	ds_read_b128 v[158:161], v142 offset:2048
	ds_read_b128 v[162:165], v142 offset:3072
	v_add_u32_e32 v142, s67, v147
	ds_read_b128 v[166:169], v142
	ds_read_b128 v[170:173], v142 offset:1024
	ds_read_b128 v[174:177], v142 offset:2048
	ds_read_b128 v[178:181], v142 offset:3072
	s_add_u32 s54, s54, 0x40000
	s_addc_u32 s55, s55, 0
	s_mov_b32 m0, s61
	v_lshl_add_u64 v[236:237], s[54:55], 0, v[136:137]
	ds_read_b128 v[182:185], v149 offset:32768
	ds_read_b128 v[186:189], v149 offset:33792
	ds_read_b128 v[190:193], v149 offset:34816
	ds_read_b128 v[202:205], v149 offset:35840
	ds_read_b128 v[206:209], v149 offset:36864
	ds_read_b128 v[210:213], v149 offset:37888
	ds_read_b128 v[214:217], v149 offset:38912
	ds_read_b128 v[218:221], v149 offset:39936
	global_load_lds_dwordx4 v[236:237], off
	v_lshl_add_u64 v[236:237], s[54:55], 0, v[132:133]
	s_mov_b32 m0, s62
	s_nop 0
	global_load_lds_dwordx4 v[236:237], off
	s_waitcnt vmcnt(8)
	s_waitcnt lgkmcnt(0)
	s_setprio 1
	s_barrier
	v_mfma_f32_16x16x32_bf16 v[126:129], v[150:153], v[182:185], v[126:129]
	v_mfma_f32_16x16x32_bf16 v[122:125], v[158:161], v[182:185], v[122:125]
	v_mfma_f32_16x16x32_bf16 v[110:113], v[150:153], v[190:193], v[110:113]
	v_mfma_f32_16x16x32_bf16 v[106:109], v[158:161], v[190:193], v[106:109]
	v_mfma_f32_16x16x32_bf16 v[94:97], v[150:153], v[206:209], v[94:97]
	v_mfma_f32_16x16x32_bf16 v[90:93], v[158:161], v[206:209], v[90:93]
	v_mfma_f32_16x16x32_bf16 v[78:81], v[150:153], v[214:217], v[78:81]
	v_mfma_f32_16x16x32_bf16 v[74:77], v[158:161], v[214:217], v[74:77]
	v_mfma_f32_16x16x32_bf16 v[126:129], v[154:157], v[186:189], v[126:129]
	v_mfma_f32_16x16x32_bf16 v[122:125], v[162:165], v[186:189], v[122:125]
	v_mfma_f32_16x16x32_bf16 v[110:113], v[154:157], v[202:205], v[110:113]
	v_mfma_f32_16x16x32_bf16 v[106:109], v[162:165], v[202:205], v[106:109]
	v_mfma_f32_16x16x32_bf16 v[94:97], v[154:157], v[210:213], v[94:97]
	v_mfma_f32_16x16x32_bf16 v[90:93], v[162:165], v[210:213], v[90:93]
	v_mfma_f32_16x16x32_bf16 v[78:81], v[154:157], v[218:221], v[78:81]
	v_mfma_f32_16x16x32_bf16 v[74:77], v[162:165], v[218:221], v[74:77]
	v_mfma_f32_16x16x32_bf16 v[118:121], v[166:169], v[182:185], v[118:121]
	v_mfma_f32_16x16x32_bf16 v[114:117], v[174:177], v[182:185], v[114:117]
	v_mfma_f32_16x16x32_bf16 v[102:105], v[166:169], v[190:193], v[102:105]
	v_mfma_f32_16x16x32_bf16 v[98:101], v[174:177], v[190:193], v[98:101]
	v_mfma_f32_16x16x32_bf16 v[86:89], v[166:169], v[206:209], v[86:89]
	v_mfma_f32_16x16x32_bf16 v[82:85], v[174:177], v[206:209], v[82:85]
	v_mfma_f32_16x16x32_bf16 v[70:73], v[166:169], v[214:217], v[70:73]
	v_mfma_f32_16x16x32_bf16 v[66:69], v[174:177], v[214:217], v[66:69]
	v_mfma_f32_16x16x32_bf16 v[118:121], v[170:173], v[186:189], v[118:121]
	v_mfma_f32_16x16x32_bf16 v[114:117], v[178:181], v[186:189], v[114:117]
	v_mfma_f32_16x16x32_bf16 v[102:105], v[170:173], v[202:205], v[102:105]
	v_mfma_f32_16x16x32_bf16 v[98:101], v[178:181], v[202:205], v[98:101]
	v_mfma_f32_16x16x32_bf16 v[86:89], v[170:173], v[210:213], v[86:89]
	v_mfma_f32_16x16x32_bf16 v[82:85], v[178:181], v[210:213], v[82:85]
	v_mfma_f32_16x16x32_bf16 v[70:73], v[170:173], v[218:221], v[70:73]
	v_mfma_f32_16x16x32_bf16 v[66:69], v[178:181], v[218:221], v[66:69]
	s_barrier
	s_setprio 0
	s_add_i32 s53, s53, s58
	v_lshl_add_u64 v[144:145], v[144:145], 0, s[10:11]
	s_mov_b32 m0, s53
	ds_read_b128 v[182:185], v149 offset:49152
	ds_read_b128 v[186:189], v149 offset:50176
	ds_read_b128 v[190:193], v149 offset:51200
	ds_read_b128 v[202:205], v149 offset:52224
	ds_read_b128 v[206:209], v149 offset:53248
	ds_read_b128 v[210:213], v149 offset:54272
	ds_read_b128 v[214:217], v149 offset:55296
	ds_read_b128 v[218:221], v149 offset:56320
	global_load_lds_dwordx4 v[144:145], off
	s_add_i32 m0, s53, 0x2000
	s_add_u32 s14, s14, 0x40080
	v_lshl_add_u64 v[144:145], v[222:223], 0, s[10:11]
	s_addc_u32 s15, s15, 0
	s_add_i32 s53, s67, s58
	global_load_lds_dwordx4 v[144:145], off
	v_lshl_add_u64 v[144:145], s[14:15], 0, v[134:135]
	s_mov_b32 m0, s53
	s_nop 0
	global_load_lds_dwordx4 v[144:145], off
	v_lshl_add_u64 v[144:145], s[14:15], 0, v[130:131]
	s_add_i32 m0, s53, 0x2000
	s_nop 0
	global_load_lds_dwordx4 v[144:145], off
	v_lshl_add_u64 v[144:145], v[232:233], 0, s[10:11]
	s_mov_b32 m0, s65
	s_nop 0
	global_load_lds_dwordx4 v[144:145], off
	v_lshl_add_u64 v[144:145], v[234:235], 0, s[10:11]
	s_mov_b32 m0, s66
	s_nop 0
	global_load_lds_dwordx4 v[144:145], off
	s_waitcnt vmcnt(8)
	s_waitcnt lgkmcnt(0)
	s_setprio 1
	s_barrier
	v_mfma_f32_16x16x32_bf16 v[62:65], v[150:153], v[182:185], v[62:65]
	v_mfma_f32_16x16x32_bf16 v[58:61], v[158:161], v[182:185], v[58:61]
	v_mfma_f32_16x16x32_bf16 v[50:53], v[150:153], v[190:193], v[50:53]
	v_mfma_f32_16x16x32_bf16 v[42:45], v[158:161], v[190:193], v[42:45]
	v_mfma_f32_16x16x32_bf16 v[34:37], v[150:153], v[206:209], v[34:37]
	v_mfma_f32_16x16x32_bf16 v[26:29], v[158:161], v[206:209], v[26:29]
	v_mfma_f32_16x16x32_bf16 v[18:21], v[150:153], v[214:217], v[18:21]
	v_mfma_f32_16x16x32_bf16 v[10:13], v[158:161], v[214:217], v[10:13]
	v_mfma_f32_16x16x32_bf16 v[62:65], v[154:157], v[186:189], v[62:65]
	v_mfma_f32_16x16x32_bf16 v[58:61], v[162:165], v[186:189], v[58:61]
	v_mfma_f32_16x16x32_bf16 v[50:53], v[154:157], v[202:205], v[50:53]
	v_mfma_f32_16x16x32_bf16 v[42:45], v[162:165], v[202:205], v[42:45]
	v_mfma_f32_16x16x32_bf16 v[34:37], v[154:157], v[210:213], v[34:37]
	v_mfma_f32_16x16x32_bf16 v[26:29], v[162:165], v[210:213], v[26:29]
	v_mfma_f32_16x16x32_bf16 v[18:21], v[154:157], v[218:221], v[18:21]
	v_mfma_f32_16x16x32_bf16 v[10:13], v[162:165], v[218:221], v[10:13]
	v_mfma_f32_16x16x32_bf16 v[54:57], v[166:169], v[182:185], v[54:57]
	v_mfma_f32_16x16x32_bf16 v[46:49], v[174:177], v[182:185], v[46:49]
	v_mfma_f32_16x16x32_bf16 v[38:41], v[166:169], v[190:193], v[38:41]
	v_mfma_f32_16x16x32_bf16 v[30:33], v[174:177], v[190:193], v[30:33]
	v_mfma_f32_16x16x32_bf16 v[22:25], v[166:169], v[206:209], v[22:25]
	v_mfma_f32_16x16x32_bf16 v[14:17], v[174:177], v[206:209], v[14:17]
	v_mfma_f32_16x16x32_bf16 v[6:9], v[166:169], v[214:217], v[6:9]
	v_mfma_f32_16x16x32_bf16 v[2:5], v[174:177], v[214:217], v[2:5]
	v_mfma_f32_16x16x32_bf16 v[54:57], v[170:173], v[186:189], v[54:57]
	v_mfma_f32_16x16x32_bf16 v[46:49], v[178:181], v[186:189], v[46:49]
	v_mfma_f32_16x16x32_bf16 v[38:41], v[170:173], v[202:205], v[38:41]
	v_mfma_f32_16x16x32_bf16 v[30:33], v[178:181], v[202:205], v[30:33]
	v_mfma_f32_16x16x32_bf16 v[22:25], v[170:173], v[210:213], v[22:25]
	v_mfma_f32_16x16x32_bf16 v[14:17], v[178:181], v[210:213], v[14:17]
	v_mfma_f32_16x16x32_bf16 v[6:9], v[170:173], v[218:221], v[6:9]
	v_mfma_f32_16x16x32_bf16 v[2:5], v[178:181], v[218:221], v[2:5]
	s_barrier
	s_setprio 0
	s_add_i32 s49, s49, 2
	s_add_u32 s37, s37, 0x100
	s_addc_u32 s47, s47, 0
	s_add_u32 s4, s4, 0x100
	s_addc_u32 s5, s5, 0
	s_cmp_gt_u32 s49, 13
	s_cbranch_scc0 .LBB0_183
	s_and_b64 vcc, exec, s[44:45]
	s_cbranch_vccz .LBB0_186
	s_barrier

.LBB0_481:
	s_add_u32 s14, s12, 0xfffc0080
	s_addc_u32 s15, s13, -1
	s_add_i32 s70, 0, 0x10000
	s_cmp_eq_u32 s53, 12
	s_cselect_b32 s59, s28, s15
	s_cselect_b32 s58, s29, s14
	s_cselect_b32 s15, s33, s51
	s_cselect_b32 s14, s36, s37
	s_add_i32 s72, 0, 0x14000
	v_add_u32_e32 v134, s70, v183
	v_add_u32_e32 v168, s72, v183
	ds_read_b128 v[114:117], v134
	ds_read_b128 v[118:121], v134 offset:1024
	ds_read_b128 v[122:125], v134 offset:2048
	ds_read_b128 v[134:137], v134 offset:3072
	ds_read_b128 v[146:149], v168
	ds_read_b128 v[150:153], v168 offset:1024
	ds_read_b128 v[164:167], v168 offset:2048
	ds_read_b128 v[168:171], v168 offset:3072
	v_lshl_add_u64 v[180:181], s[12:13], 0, v[162:163]
	s_add_i32 m0, s63, 0xc000
	ds_read_b128 v[172:175], v185
	ds_read_b128 v[176:179], v185 offset:1024
	ds_read_b128 v[186:189], v185 offset:2048
	ds_read_b128 v[190:193], v185 offset:3072
	ds_read_b128 v[202:205], v185 offset:4096
	ds_read_b128 v[206:209], v185 offset:5120
	ds_read_b128 v[210:213], v185 offset:6144
	ds_read_b128 v[214:217], v185 offset:7168
	global_load_lds_dwordx4 v[180:181], off
	v_lshl_add_u64 v[180:181], s[12:13], 0, v[160:161]
	s_add_i32 m0, s63, 0xe000
	s_nop 0
	global_load_lds_dwordx4 v[180:181], off
	s_waitcnt vmcnt(8)
	s_waitcnt lgkmcnt(0)
	s_setprio 1
	s_barrier
	v_mfma_f32_16x16x32_bf16 v[142:145], v[114:117], v[172:175], v[142:145]
	v_mfma_f32_16x16x32_bf16 v[138:141], v[122:125], v[172:175], v[138:141]
	v_mfma_f32_16x16x32_bf16 v[110:113], v[114:117], v[186:189], v[110:113]
	v_mfma_f32_16x16x32_bf16 v[106:109], v[122:125], v[186:189], v[106:109]
	v_mfma_f32_16x16x32_bf16 v[94:97], v[114:117], v[202:205], v[94:97]
	v_mfma_f32_16x16x32_bf16 v[90:93], v[122:125], v[202:205], v[90:93]
	v_mfma_f32_16x16x32_bf16 v[78:81], v[114:117], v[210:213], v[78:81]
	v_mfma_f32_16x16x32_bf16 v[74:77], v[122:125], v[210:213], v[74:77]
	v_mfma_f32_16x16x32_bf16 v[142:145], v[118:121], v[176:179], v[142:145]
	v_mfma_f32_16x16x32_bf16 v[138:141], v[134:137], v[176:179], v[138:141]
	v_mfma_f32_16x16x32_bf16 v[110:113], v[118:121], v[190:193], v[110:113]
	v_mfma_f32_16x16x32_bf16 v[106:109], v[134:137], v[190:193], v[106:109]
	v_mfma_f32_16x16x32_bf16 v[94:97], v[118:121], v[206:209], v[94:97]
	v_mfma_f32_16x16x32_bf16 v[90:93], v[134:137], v[206:209], v[90:93]
	v_mfma_f32_16x16x32_bf16 v[78:81], v[118:121], v[214:217], v[78:81]
	v_mfma_f32_16x16x32_bf16 v[74:77], v[134:137], v[214:217], v[74:77]
	v_mfma_f32_16x16x32_bf16 v[130:133], v[146:149], v[172:175], v[130:133]
	v_mfma_f32_16x16x32_bf16 v[126:129], v[164:167], v[172:175], v[126:129]
	v_mfma_f32_16x16x32_bf16 v[102:105], v[146:149], v[186:189], v[102:105]
	v_mfma_f32_16x16x32_bf16 v[98:101], v[164:167], v[186:189], v[98:101]
	v_mfma_f32_16x16x32_bf16 v[86:89], v[146:149], v[202:205], v[86:89]
	v_mfma_f32_16x16x32_bf16 v[82:85], v[164:167], v[202:205], v[82:85]
	v_mfma_f32_16x16x32_bf16 v[70:73], v[146:149], v[210:213], v[70:73]
	v_mfma_f32_16x16x32_bf16 v[66:69], v[164:167], v[210:213], v[66:69]
	v_mfma_f32_16x16x32_bf16 v[130:133], v[150:153], v[176:179], v[130:133]
	v_mfma_f32_16x16x32_bf16 v[126:129], v[168:171], v[176:179], v[126:129]
	v_mfma_f32_16x16x32_bf16 v[102:105], v[150:153], v[190:193], v[102:105]
	v_mfma_f32_16x16x32_bf16 v[98:101], v[168:171], v[190:193], v[98:101]
	v_mfma_f32_16x16x32_bf16 v[86:89], v[150:153], v[206:209], v[86:89]
	v_mfma_f32_16x16x32_bf16 v[82:85], v[168:171], v[206:209], v[82:85]
	v_mfma_f32_16x16x32_bf16 v[70:73], v[150:153], v[214:217], v[70:73]
	v_mfma_f32_16x16x32_bf16 v[66:69], v[168:171], v[214:217], v[66:69]
	s_barrier
	s_setprio 0
	s_add_i32 s70, s70, s62
	v_lshl_add_u64 v[180:181], s[14:15], 0, v[0:1]
	s_mov_b32 m0, s70
	ds_read_b128 v[172:175], v185 offset:16384
	ds_read_b128 v[176:179], v185 offset:17408
	ds_read_b128 v[186:189], v185 offset:18432
	ds_read_b128 v[190:193], v185 offset:19456
	ds_read_b128 v[202:205], v185 offset:20480
	ds_read_b128 v[206:209], v185 offset:21504
	ds_read_b128 v[210:213], v185 offset:22528
	ds_read_b128 v[214:217], v185 offset:23552
	global_load_lds_dwordx4 v[180:181], off
	s_add_i32 m0, s70, 0x2000
	s_add_u32 s70, s14, 0x40000
	v_lshl_add_u64 v[218:219], s[14:15], 0, v[154:155]
	s_addc_u32 s71, s15, 0
	s_add_i32 s72, s72, s62
	global_load_lds_dwordx4 v[218:219], off
	v_lshl_add_u64 v[220:221], s[70:71], 0, v[0:1]
	s_mov_b32 m0, s72
	v_lshl_add_u64 v[222:223], s[58:59], 0, v[156:157]
	global_load_lds_dwordx4 v[220:221], off
	v_lshl_add_u64 v[220:221], s[70:71], 0, v[154:155]
	s_add_i32 m0, s72, 0x2000
	s_nop 0
	global_load_lds_dwordx4 v[220:221], off
	v_lshl_add_u64 v[220:221], s[58:59], 0, v[158:159]
	s_mov_b32 m0, s63
	s_nop 0
	global_load_lds_dwordx4 v[220:221], off
	s_mov_b32 m0, s64
	s_nop 0
	global_load_lds_dwordx4 v[222:223], off
	s_waitcnt vmcnt(8)
	s_waitcnt lgkmcnt(0)
	s_setprio 1
	s_barrier
	v_mfma_f32_16x16x32_bf16 v[62:65], v[114:117], v[172:175], v[62:65]
	v_mfma_f32_16x16x32_bf16 v[58:61], v[122:125], v[172:175], v[58:61]
	v_mfma_f32_16x16x32_bf16 v[46:49], v[114:117], v[186:189], v[46:49]
	v_mfma_f32_16x16x32_bf16 v[42:45], v[122:125], v[186:189], v[42:45]
	v_mfma_f32_16x16x32_bf16 v[30:33], v[114:117], v[202:205], v[30:33]
	v_mfma_f32_16x16x32_bf16 v[26:29], v[122:125], v[202:205], v[26:29]
	v_mfma_f32_16x16x32_bf16 v[14:17], v[114:117], v[210:213], v[14:17]
	v_mfma_f32_16x16x32_bf16 v[10:13], v[122:125], v[210:213], v[10:13]
	v_mfma_f32_16x16x32_bf16 v[62:65], v[118:121], v[176:179], v[62:65]
	v_mfma_f32_16x16x32_bf16 v[58:61], v[134:137], v[176:179], v[58:61]
	v_mfma_f32_16x16x32_bf16 v[46:49], v[118:121], v[190:193], v[46:49]
	v_mfma_f32_16x16x32_bf16 v[42:45], v[134:137], v[190:193], v[42:45]
	v_mfma_f32_16x16x32_bf16 v[30:33], v[118:121], v[206:209], v[30:33]
	v_mfma_f32_16x16x32_bf16 v[26:29], v[134:137], v[206:209], v[26:29]
	v_mfma_f32_16x16x32_bf16 v[14:17], v[118:121], v[214:217], v[14:17]
	v_mfma_f32_16x16x32_bf16 v[10:13], v[134:137], v[214:217], v[10:13]
	v_mfma_f32_16x16x32_bf16 v[54:57], v[146:149], v[172:175], v[54:57]
	v_mfma_f32_16x16x32_bf16 v[50:53], v[164:167], v[172:175], v[50:53]
	v_mfma_f32_16x16x32_bf16 v[38:41], v[146:149], v[186:189], v[38:41]
	v_mfma_f32_16x16x32_bf16 v[34:37], v[164:167], v[186:189], v[34:37]
	v_mfma_f32_16x16x32_bf16 v[22:25], v[146:149], v[202:205], v[22:25]
	v_mfma_f32_16x16x32_bf16 v[18:21], v[164:167], v[202:205], v[18:21]
	v_mfma_f32_16x16x32_bf16 v[6:9], v[146:149], v[210:213], v[6:9]
	v_mfma_f32_16x16x32_bf16 v[2:5], v[164:167], v[210:213], v[2:5]
	v_mfma_f32_16x16x32_bf16 v[54:57], v[150:153], v[176:179], v[54:57]
	v_mfma_f32_16x16x32_bf16 v[50:53], v[168:171], v[176:179], v[50:53]
	v_mfma_f32_16x16x32_bf16 v[38:41], v[150:153], v[190:193], v[38:41]
	v_mfma_f32_16x16x32_bf16 v[34:37], v[168:171], v[190:193], v[34:37]
	v_mfma_f32_16x16x32_bf16 v[22:25], v[150:153], v[206:209], v[22:25]
	v_mfma_f32_16x16x32_bf16 v[18:21], v[168:171], v[206:209], v[18:21]
	v_mfma_f32_16x16x32_bf16 v[6:9], v[150:153], v[214:217], v[6:9]
	v_mfma_f32_16x16x32_bf16 v[2:5], v[168:171], v[214:217], v[2:5]
	s_barrier
	s_setprio 0
	s_add_i32 s70, 0, 0x18000
	s_add_i32 s71, 0, 0x1c000
	v_add_u32_e32 v134, s70, v183
	v_add_u32_e32 v168, s71, v183
	ds_read_b128 v[114:117], v134
	ds_read_b128 v[118:121], v134 offset:1024
	ds_read_b128 v[122:125], v134 offset:2048
	ds_read_b128 v[134:137], v134 offset:3072
	ds_read_b128 v[146:149], v168
	ds_read_b128 v[150:153], v168 offset:1024
	ds_read_b128 v[164:167], v168 offset:2048
	ds_read_b128 v[168:171], v168 offset:3072
	s_add_u32 s58, s58, 0x40000
	s_addc_u32 s59, s59, 0
	s_mov_b32 m0, s65
	v_lshl_add_u64 v[232:233], s[58:59], 0, v[158:159]
	ds_read_b128 v[172:175], v185 offset:32768
	ds_read_b128 v[176:179], v185 offset:33792
	ds_read_b128 v[186:189], v185 offset:34816
	ds_read_b128 v[190:193], v185 offset:35840
	ds_read_b128 v[202:205], v185 offset:36864
	ds_read_b128 v[206:209], v185 offset:37888
	ds_read_b128 v[210:213], v185 offset:38912
	ds_read_b128 v[214:217], v185 offset:39936
	global_load_lds_dwordx4 v[232:233], off
	v_lshl_add_u64 v[232:233], s[58:59], 0, v[156:157]
	s_mov_b32 m0, s66
	s_nop 0
	global_load_lds_dwordx4 v[232:233], off
	s_waitcnt vmcnt(8)
	s_waitcnt lgkmcnt(0)
	s_setprio 1
	s_barrier
	v_mfma_f32_16x16x32_bf16 v[142:145], v[114:117], v[172:175], v[142:145]
	v_mfma_f32_16x16x32_bf16 v[138:141], v[122:125], v[172:175], v[138:141]
	v_mfma_f32_16x16x32_bf16 v[110:113], v[114:117], v[186:189], v[110:113]
	v_mfma_f32_16x16x32_bf16 v[106:109], v[122:125], v[186:189], v[106:109]
	v_mfma_f32_16x16x32_bf16 v[94:97], v[114:117], v[202:205], v[94:97]
	v_mfma_f32_16x16x32_bf16 v[90:93], v[122:125], v[202:205], v[90:93]
	v_mfma_f32_16x16x32_bf16 v[78:81], v[114:117], v[210:213], v[78:81]
	v_mfma_f32_16x16x32_bf16 v[74:77], v[122:125], v[210:213], v[74:77]
	v_mfma_f32_16x16x32_bf16 v[142:145], v[118:121], v[176:179], v[142:145]
	v_mfma_f32_16x16x32_bf16 v[138:141], v[134:137], v[176:179], v[138:141]
	v_mfma_f32_16x16x32_bf16 v[110:113], v[118:121], v[190:193], v[110:113]
	v_mfma_f32_16x16x32_bf16 v[106:109], v[134:137], v[190:193], v[106:109]
	v_mfma_f32_16x16x32_bf16 v[94:97], v[118:121], v[206:209], v[94:97]
	v_mfma_f32_16x16x32_bf16 v[90:93], v[134:137], v[206:209], v[90:93]
	v_mfma_f32_16x16x32_bf16 v[78:81], v[118:121], v[214:217], v[78:81]
	v_mfma_f32_16x16x32_bf16 v[74:77], v[134:137], v[214:217], v[74:77]
	v_mfma_f32_16x16x32_bf16 v[130:133], v[146:149], v[172:175], v[130:133]
	v_mfma_f32_16x16x32_bf16 v[126:129], v[164:167], v[172:175], v[126:129]
	v_mfma_f32_16x16x32_bf16 v[102:105], v[146:149], v[186:189], v[102:105]
	v_mfma_f32_16x16x32_bf16 v[98:101], v[164:167], v[186:189], v[98:101]
	v_mfma_f32_16x16x32_bf16 v[86:89], v[146:149], v[202:205], v[86:89]
	v_mfma_f32_16x16x32_bf16 v[82:85], v[164:167], v[202:205], v[82:85]
	v_mfma_f32_16x16x32_bf16 v[70:73], v[146:149], v[210:213], v[70:73]
	v_mfma_f32_16x16x32_bf16 v[66:69], v[164:167], v[210:213], v[66:69]
	v_mfma_f32_16x16x32_bf16 v[130:133], v[150:153], v[176:179], v[130:133]
	v_mfma_f32_16x16x32_bf16 v[126:129], v[168:171], v[176:179], v[126:129]
	v_mfma_f32_16x16x32_bf16 v[102:105], v[150:153], v[190:193], v[102:105]
	v_mfma_f32_16x16x32_bf16 v[98:101], v[168:171], v[190:193], v[98:101]
	v_mfma_f32_16x16x32_bf16 v[86:89], v[150:153], v[206:209], v[86:89]
	v_mfma_f32_16x16x32_bf16 v[82:85], v[168:171], v[206:209], v[82:85]
	v_mfma_f32_16x16x32_bf16 v[70:73], v[150:153], v[214:217], v[70:73]
	v_mfma_f32_16x16x32_bf16 v[66:69], v[168:171], v[214:217], v[66:69]
	s_barrier
	s_setprio 0
	s_add_i32 s58, s70, s62
	v_lshl_add_u64 v[180:181], v[180:181], 0, s[10:11]
	s_mov_b32 m0, s58
	ds_read_b128 v[172:175], v185 offset:49152
	ds_read_b128 v[176:179], v185 offset:50176
	ds_read_b128 v[186:189], v185 offset:51200
	ds_read_b128 v[190:193], v185 offset:52224
	ds_read_b128 v[202:205], v185 offset:53248
	ds_read_b128 v[206:209], v185 offset:54272
	ds_read_b128 v[210:213], v185 offset:55296
	ds_read_b128 v[214:217], v185 offset:56320
	global_load_lds_dwordx4 v[180:181], off
	s_add_i32 m0, s58, 0x2000
	s_add_u32 s14, s14, 0x40080
	v_lshl_add_u64 v[180:181], v[218:219], 0, s[10:11]
	s_addc_u32 s15, s15, 0
	s_add_i32 s58, s71, s62
	global_load_lds_dwordx4 v[180:181], off
	v_lshl_add_u64 v[180:181], s[14:15], 0, v[0:1]
	s_mov_b32 m0, s58
	s_nop 0
	global_load_lds_dwordx4 v[180:181], off
	v_lshl_add_u64 v[180:181], s[14:15], 0, v[154:155]
	s_add_i32 m0, s58, 0x2000
	s_nop 0
	global_load_lds_dwordx4 v[180:181], off
	v_lshl_add_u64 v[180:181], v[220:221], 0, s[10:11]
	s_mov_b32 m0, s67
	s_nop 0
	global_load_lds_dwordx4 v[180:181], off
	v_lshl_add_u64 v[180:181], v[222:223], 0, s[10:11]
	s_mov_b32 m0, s68
	s_nop 0
	global_load_lds_dwordx4 v[180:181], off
	s_waitcnt vmcnt(8)
	s_waitcnt lgkmcnt(0)
	s_setprio 1
	s_barrier
	v_mfma_f32_16x16x32_bf16 v[62:65], v[114:117], v[172:175], v[62:65]
	v_mfma_f32_16x16x32_bf16 v[58:61], v[122:125], v[172:175], v[58:61]
	v_mfma_f32_16x16x32_bf16 v[46:49], v[114:117], v[186:189], v[46:49]
	v_mfma_f32_16x16x32_bf16 v[42:45], v[122:125], v[186:189], v[42:45]
	v_mfma_f32_16x16x32_bf16 v[30:33], v[114:117], v[202:205], v[30:33]
	v_mfma_f32_16x16x32_bf16 v[26:29], v[122:125], v[202:205], v[26:29]
	v_mfma_f32_16x16x32_bf16 v[14:17], v[114:117], v[210:213], v[14:17]
	v_mfma_f32_16x16x32_bf16 v[10:13], v[122:125], v[210:213], v[10:13]
	v_mfma_f32_16x16x32_bf16 v[62:65], v[118:121], v[176:179], v[62:65]
	v_mfma_f32_16x16x32_bf16 v[58:61], v[134:137], v[176:179], v[58:61]
	v_mfma_f32_16x16x32_bf16 v[46:49], v[118:121], v[190:193], v[46:49]
	v_mfma_f32_16x16x32_bf16 v[42:45], v[134:137], v[190:193], v[42:45]
	v_mfma_f32_16x16x32_bf16 v[30:33], v[118:121], v[206:209], v[30:33]
	v_mfma_f32_16x16x32_bf16 v[26:29], v[134:137], v[206:209], v[26:29]
	v_mfma_f32_16x16x32_bf16 v[14:17], v[118:121], v[214:217], v[14:17]
	v_mfma_f32_16x16x32_bf16 v[10:13], v[134:137], v[214:217], v[10:13]
	v_mfma_f32_16x16x32_bf16 v[54:57], v[146:149], v[172:175], v[54:57]
	v_mfma_f32_16x16x32_bf16 v[50:53], v[164:167], v[172:175], v[50:53]
	v_mfma_f32_16x16x32_bf16 v[38:41], v[146:149], v[186:189], v[38:41]
	v_mfma_f32_16x16x32_bf16 v[34:37], v[164:167], v[186:189], v[34:37]
	v_mfma_f32_16x16x32_bf16 v[22:25], v[146:149], v[202:205], v[22:25]
	v_mfma_f32_16x16x32_bf16 v[18:21], v[164:167], v[202:205], v[18:21]
	v_mfma_f32_16x16x32_bf16 v[6:9], v[146:149], v[210:213], v[6:9]
	v_mfma_f32_16x16x32_bf16 v[2:5], v[164:167], v[210:213], v[2:5]
	v_mfma_f32_16x16x32_bf16 v[54:57], v[150:153], v[176:179], v[54:57]
	v_mfma_f32_16x16x32_bf16 v[50:53], v[168:171], v[176:179], v[50:53]
	v_mfma_f32_16x16x32_bf16 v[38:41], v[150:153], v[190:193], v[38:41]
	v_mfma_f32_16x16x32_bf16 v[34:37], v[168:171], v[190:193], v[34:37]
	v_mfma_f32_16x16x32_bf16 v[22:25], v[150:153], v[206:209], v[22:25]
	v_mfma_f32_16x16x32_bf16 v[18:21], v[168:171], v[206:209], v[18:21]
	v_mfma_f32_16x16x32_bf16 v[6:9], v[150:153], v[214:217], v[6:9]
	v_mfma_f32_16x16x32_bf16 v[2:5], v[168:171], v[214:217], v[2:5]
	s_barrier
	s_setprio 0
	s_add_i32 s53, s53, 2
	s_add_u32 s37, s37, 0x100
	s_addc_u32 s51, s51, 0
	s_add_u32 s12, s12, 0x100
	s_addc_u32 s13, s13, 0
	s_cmp_gt_u32 s53, 13
	s_cbranch_scc0 .LBB0_481
	s_and_b64 vcc, exec, s[48:49]
	s_cbranch_vccz .LBB0_484
	s_barrier

.LBB0_561:
	s_add_u32 s14, s12, 0xfffc0080
	s_addc_u32 s15, s13, -1
	s_add_i32 s66, 0, 0x10000
	s_cmp_eq_u32 s49, 12
	s_cselect_b32 s55, s28, s15
	s_cselect_b32 s54, s29, s14
	v_add_u32_e32 v140, s66, v145
	s_cselect_b32 s15, s33, s47
	s_cselect_b32 s14, s36, s37
	s_add_i32 s68, 0, 0x14000
	ds_read_b128 v[150:153], v140
	ds_read_b128 v[154:157], v140 offset:1024
	ds_read_b128 v[158:161], v140 offset:2048
	ds_read_b128 v[162:165], v140 offset:3072
	v_add_u32_e32 v140, s68, v145
	ds_read_b128 v[166:169], v140
	ds_read_b128 v[170:173], v140 offset:1024
	ds_read_b128 v[174:177], v140 offset:2048
	ds_read_b128 v[178:181], v140 offset:3072
	v_lshl_add_u64 v[142:143], s[12:13], 0, v[138:139]
	s_add_i32 m0, s59, 0xc000
	ds_read_b128 v[182:185], v149
	ds_read_b128 v[186:189], v149 offset:1024
	ds_read_b128 v[190:193], v149 offset:2048
	ds_read_b128 v[202:205], v149 offset:3072
	ds_read_b128 v[206:209], v149 offset:4096
	ds_read_b128 v[210:213], v149 offset:5120
	ds_read_b128 v[214:217], v149 offset:6144
	ds_read_b128 v[218:221], v149 offset:7168
	global_load_lds_dwordx4 v[142:143], off
	v_lshl_add_u64 v[142:143], s[12:13], 0, v[136:137]
	s_add_i32 m0, s59, 0xe000
	s_nop 0
	global_load_lds_dwordx4 v[142:143], off
	s_waitcnt vmcnt(8)
	s_waitcnt lgkmcnt(0)
	s_setprio 1
	s_barrier
	v_mfma_f32_16x16x32_bf16 v[126:129], v[150:153], v[182:185], v[126:129]
	v_mfma_f32_16x16x32_bf16 v[122:125], v[158:161], v[182:185], v[122:125]
	v_mfma_f32_16x16x32_bf16 v[110:113], v[150:153], v[190:193], v[110:113]
	v_mfma_f32_16x16x32_bf16 v[106:109], v[158:161], v[190:193], v[106:109]
	v_mfma_f32_16x16x32_bf16 v[94:97], v[150:153], v[206:209], v[94:97]
	v_mfma_f32_16x16x32_bf16 v[90:93], v[158:161], v[206:209], v[90:93]
	v_mfma_f32_16x16x32_bf16 v[78:81], v[150:153], v[214:217], v[78:81]
	v_mfma_f32_16x16x32_bf16 v[74:77], v[158:161], v[214:217], v[74:77]
	v_mfma_f32_16x16x32_bf16 v[126:129], v[154:157], v[186:189], v[126:129]
	v_mfma_f32_16x16x32_bf16 v[122:125], v[162:165], v[186:189], v[122:125]
	v_mfma_f32_16x16x32_bf16 v[110:113], v[154:157], v[202:205], v[110:113]
	v_mfma_f32_16x16x32_bf16 v[106:109], v[162:165], v[202:205], v[106:109]
	v_mfma_f32_16x16x32_bf16 v[94:97], v[154:157], v[210:213], v[94:97]
	v_mfma_f32_16x16x32_bf16 v[90:93], v[162:165], v[210:213], v[90:93]
	v_mfma_f32_16x16x32_bf16 v[78:81], v[154:157], v[218:221], v[78:81]
	v_mfma_f32_16x16x32_bf16 v[74:77], v[162:165], v[218:221], v[74:77]
	v_mfma_f32_16x16x32_bf16 v[118:121], v[166:169], v[182:185], v[118:121]
	v_mfma_f32_16x16x32_bf16 v[114:117], v[174:177], v[182:185], v[114:117]
	v_mfma_f32_16x16x32_bf16 v[102:105], v[166:169], v[190:193], v[102:105]
	v_mfma_f32_16x16x32_bf16 v[98:101], v[174:177], v[190:193], v[98:101]
	v_mfma_f32_16x16x32_bf16 v[86:89], v[166:169], v[206:209], v[86:89]
	v_mfma_f32_16x16x32_bf16 v[82:85], v[174:177], v[206:209], v[82:85]
	v_mfma_f32_16x16x32_bf16 v[70:73], v[166:169], v[214:217], v[70:73]
	v_mfma_f32_16x16x32_bf16 v[66:69], v[174:177], v[214:217], v[66:69]
	v_mfma_f32_16x16x32_bf16 v[118:121], v[170:173], v[186:189], v[118:121]
	v_mfma_f32_16x16x32_bf16 v[114:117], v[178:181], v[186:189], v[114:117]
	v_mfma_f32_16x16x32_bf16 v[102:105], v[170:173], v[202:205], v[102:105]
	v_mfma_f32_16x16x32_bf16 v[98:101], v[178:181], v[202:205], v[98:101]
	v_mfma_f32_16x16x32_bf16 v[86:89], v[170:173], v[210:213], v[86:89]
	v_mfma_f32_16x16x32_bf16 v[82:85], v[178:181], v[210:213], v[82:85]
	v_mfma_f32_16x16x32_bf16 v[70:73], v[170:173], v[218:221], v[70:73]
	v_mfma_f32_16x16x32_bf16 v[66:69], v[178:181], v[218:221], v[66:69]
	s_barrier
	s_setprio 0
	s_add_i32 s66, s66, s58
	v_lshl_add_u64 v[142:143], s[14:15], 0, v[0:1]
	s_mov_b32 m0, s66
	ds_read_b128 v[182:185], v149 offset:16384
	ds_read_b128 v[186:189], v149 offset:17408
	ds_read_b128 v[190:193], v149 offset:18432
	ds_read_b128 v[202:205], v149 offset:19456
	ds_read_b128 v[206:209], v149 offset:20480
	ds_read_b128 v[210:213], v149 offset:21504
	ds_read_b128 v[214:217], v149 offset:22528
	ds_read_b128 v[218:221], v149 offset:23552
	global_load_lds_dwordx4 v[142:143], off
	s_add_i32 m0, s66, 0x2000
	s_add_u32 s66, s14, 0x40000
	v_lshl_add_u64 v[222:223], s[14:15], 0, v[130:131]
	s_addc_u32 s67, s15, 0
	s_add_i32 s68, s68, s58
	global_load_lds_dwordx4 v[222:223], off
	v_lshl_add_u64 v[232:233], s[66:67], 0, v[0:1]
	s_mov_b32 m0, s68
	v_lshl_add_u64 v[234:235], s[54:55], 0, v[132:133]
	global_load_lds_dwordx4 v[232:233], off
	v_lshl_add_u64 v[232:233], s[66:67], 0, v[130:131]
	s_add_i32 m0, s68, 0x2000
	s_nop 0
	global_load_lds_dwordx4 v[232:233], off
	v_lshl_add_u64 v[232:233], s[54:55], 0, v[134:135]
	s_mov_b32 m0, s59
	s_nop 0
	global_load_lds_dwordx4 v[232:233], off
	s_mov_b32 m0, s60
	s_nop 0
	global_load_lds_dwordx4 v[234:235], off
	s_waitcnt vmcnt(8)
	s_waitcnt lgkmcnt(0)
	s_setprio 1
	s_barrier
	v_mfma_f32_16x16x32_bf16 v[62:65], v[150:153], v[182:185], v[62:65]
	v_mfma_f32_16x16x32_bf16 v[58:61], v[158:161], v[182:185], v[58:61]
	v_mfma_f32_16x16x32_bf16 v[46:49], v[150:153], v[190:193], v[46:49]
	v_mfma_f32_16x16x32_bf16 v[42:45], v[158:161], v[190:193], v[42:45]
	v_mfma_f32_16x16x32_bf16 v[30:33], v[150:153], v[206:209], v[30:33]
	v_mfma_f32_16x16x32_bf16 v[26:29], v[158:161], v[206:209], v[26:29]
	v_mfma_f32_16x16x32_bf16 v[14:17], v[150:153], v[214:217], v[14:17]
	v_mfma_f32_16x16x32_bf16 v[10:13], v[158:161], v[214:217], v[10:13]
	v_mfma_f32_16x16x32_bf16 v[62:65], v[154:157], v[186:189], v[62:65]
	v_mfma_f32_16x16x32_bf16 v[58:61], v[162:165], v[186:189], v[58:61]
	v_mfma_f32_16x16x32_bf16 v[46:49], v[154:157], v[202:205], v[46:49]
	v_mfma_f32_16x16x32_bf16 v[42:45], v[162:165], v[202:205], v[42:45]
	v_mfma_f32_16x16x32_bf16 v[30:33], v[154:157], v[210:213], v[30:33]
	v_mfma_f32_16x16x32_bf16 v[26:29], v[162:165], v[210:213], v[26:29]
	v_mfma_f32_16x16x32_bf16 v[14:17], v[154:157], v[218:221], v[14:17]
	v_mfma_f32_16x16x32_bf16 v[10:13], v[162:165], v[218:221], v[10:13]
	v_mfma_f32_16x16x32_bf16 v[54:57], v[166:169], v[182:185], v[54:57]
	v_mfma_f32_16x16x32_bf16 v[50:53], v[174:177], v[182:185], v[50:53]
	v_mfma_f32_16x16x32_bf16 v[38:41], v[166:169], v[190:193], v[38:41]
	v_mfma_f32_16x16x32_bf16 v[34:37], v[174:177], v[190:193], v[34:37]
	v_mfma_f32_16x16x32_bf16 v[22:25], v[166:169], v[206:209], v[22:25]
	v_mfma_f32_16x16x32_bf16 v[18:21], v[174:177], v[206:209], v[18:21]
	v_mfma_f32_16x16x32_bf16 v[6:9], v[166:169], v[214:217], v[6:9]
	v_mfma_f32_16x16x32_bf16 v[2:5], v[174:177], v[214:217], v[2:5]
	v_mfma_f32_16x16x32_bf16 v[54:57], v[170:173], v[186:189], v[54:57]
	v_mfma_f32_16x16x32_bf16 v[50:53], v[178:181], v[186:189], v[50:53]
	v_mfma_f32_16x16x32_bf16 v[38:41], v[170:173], v[202:205], v[38:41]
	v_mfma_f32_16x16x32_bf16 v[34:37], v[178:181], v[202:205], v[34:37]
	v_mfma_f32_16x16x32_bf16 v[22:25], v[170:173], v[210:213], v[22:25]
	v_mfma_f32_16x16x32_bf16 v[18:21], v[178:181], v[210:213], v[18:21]
	v_mfma_f32_16x16x32_bf16 v[6:9], v[170:173], v[218:221], v[6:9]
	v_mfma_f32_16x16x32_bf16 v[2:5], v[178:181], v[218:221], v[2:5]
	s_barrier
	s_setprio 0
	s_add_i32 s66, 0, 0x18000
	v_add_u32_e32 v140, s66, v145
	s_add_i32 s67, 0, 0x1c000
	ds_read_b128 v[150:153], v140
	ds_read_b128 v[154:157], v140 offset:1024
	ds_read_b128 v[158:161], v140 offset:2048
	ds_read_b128 v[162:165], v140 offset:3072
	v_add_u32_e32 v140, s67, v145
	ds_read_b128 v[166:169], v140
	ds_read_b128 v[170:173], v140 offset:1024
	ds_read_b128 v[174:177], v140 offset:2048
	ds_read_b128 v[178:181], v140 offset:3072
	s_add_u32 s54, s54, 0x40000
	s_addc_u32 s55, s55, 0
	s_mov_b32 m0, s61
	v_lshl_add_u64 v[236:237], s[54:55], 0, v[134:135]
	ds_read_b128 v[182:185], v149 offset:32768
	ds_read_b128 v[186:189], v149 offset:33792
	ds_read_b128 v[190:193], v149 offset:34816
	ds_read_b128 v[202:205], v149 offset:35840
	ds_read_b128 v[206:209], v149 offset:36864
	ds_read_b128 v[210:213], v149 offset:37888
	ds_read_b128 v[214:217], v149 offset:38912
	ds_read_b128 v[218:221], v149 offset:39936
	global_load_lds_dwordx4 v[236:237], off
	v_lshl_add_u64 v[236:237], s[54:55], 0, v[132:133]
	s_mov_b32 m0, s62
	s_nop 0
	global_load_lds_dwordx4 v[236:237], off
	s_waitcnt vmcnt(8)
	s_waitcnt lgkmcnt(0)
	s_setprio 1
	s_barrier
	v_mfma_f32_16x16x32_bf16 v[126:129], v[150:153], v[182:185], v[126:129]
	v_mfma_f32_16x16x32_bf16 v[122:125], v[158:161], v[182:185], v[122:125]
	v_mfma_f32_16x16x32_bf16 v[110:113], v[150:153], v[190:193], v[110:113]
	v_mfma_f32_16x16x32_bf16 v[106:109], v[158:161], v[190:193], v[106:109]
	v_mfma_f32_16x16x32_bf16 v[94:97], v[150:153], v[206:209], v[94:97]
	v_mfma_f32_16x16x32_bf16 v[90:93], v[158:161], v[206:209], v[90:93]
	v_mfma_f32_16x16x32_bf16 v[78:81], v[150:153], v[214:217], v[78:81]
	v_mfma_f32_16x16x32_bf16 v[74:77], v[158:161], v[214:217], v[74:77]
	v_mfma_f32_16x16x32_bf16 v[126:129], v[154:157], v[186:189], v[126:129]
	v_mfma_f32_16x16x32_bf16 v[122:125], v[162:165], v[186:189], v[122:125]
	v_mfma_f32_16x16x32_bf16 v[110:113], v[154:157], v[202:205], v[110:113]
	v_mfma_f32_16x16x32_bf16 v[106:109], v[162:165], v[202:205], v[106:109]
	v_mfma_f32_16x16x32_bf16 v[94:97], v[154:157], v[210:213], v[94:97]
	v_mfma_f32_16x16x32_bf16 v[90:93], v[162:165], v[210:213], v[90:93]
	v_mfma_f32_16x16x32_bf16 v[78:81], v[154:157], v[218:221], v[78:81]
	v_mfma_f32_16x16x32_bf16 v[74:77], v[162:165], v[218:221], v[74:77]
	v_mfma_f32_16x16x32_bf16 v[118:121], v[166:169], v[182:185], v[118:121]
	v_mfma_f32_16x16x32_bf16 v[114:117], v[174:177], v[182:185], v[114:117]
	v_mfma_f32_16x16x32_bf16 v[102:105], v[166:169], v[190:193], v[102:105]
	v_mfma_f32_16x16x32_bf16 v[98:101], v[174:177], v[190:193], v[98:101]
	v_mfma_f32_16x16x32_bf16 v[86:89], v[166:169], v[206:209], v[86:89]
	v_mfma_f32_16x16x32_bf16 v[82:85], v[174:177], v[206:209], v[82:85]
	v_mfma_f32_16x16x32_bf16 v[70:73], v[166:169], v[214:217], v[70:73]
	v_mfma_f32_16x16x32_bf16 v[66:69], v[174:177], v[214:217], v[66:69]
	v_mfma_f32_16x16x32_bf16 v[118:121], v[170:173], v[186:189], v[118:121]
	v_mfma_f32_16x16x32_bf16 v[114:117], v[178:181], v[186:189], v[114:117]
	v_mfma_f32_16x16x32_bf16 v[102:105], v[170:173], v[202:205], v[102:105]
	v_mfma_f32_16x16x32_bf16 v[98:101], v[178:181], v[202:205], v[98:101]
	v_mfma_f32_16x16x32_bf16 v[86:89], v[170:173], v[210:213], v[86:89]
	v_mfma_f32_16x16x32_bf16 v[82:85], v[178:181], v[210:213], v[82:85]
	v_mfma_f32_16x16x32_bf16 v[70:73], v[170:173], v[218:221], v[70:73]
	v_mfma_f32_16x16x32_bf16 v[66:69], v[178:181], v[218:221], v[66:69]
	s_barrier
	s_setprio 0
	s_add_i32 s54, s66, s58
	v_lshl_add_u64 v[142:143], v[142:143], 0, s[10:11]
	s_mov_b32 m0, s54
	ds_read_b128 v[182:185], v149 offset:49152
	ds_read_b128 v[186:189], v149 offset:50176
	ds_read_b128 v[190:193], v149 offset:51200
	ds_read_b128 v[202:205], v149 offset:52224
	ds_read_b128 v[206:209], v149 offset:53248
	ds_read_b128 v[210:213], v149 offset:54272
	ds_read_b128 v[214:217], v149 offset:55296
	ds_read_b128 v[218:221], v149 offset:56320
	global_load_lds_dwordx4 v[142:143], off
	s_add_i32 m0, s54, 0x2000
	s_add_u32 s14, s14, 0x40080
	v_lshl_add_u64 v[142:143], v[222:223], 0, s[10:11]
	s_addc_u32 s15, s15, 0
	s_add_i32 s54, s67, s58
	global_load_lds_dwordx4 v[142:143], off
	v_lshl_add_u64 v[142:143], s[14:15], 0, v[0:1]
	s_mov_b32 m0, s54
	s_nop 0
	global_load_lds_dwordx4 v[142:143], off
	v_lshl_add_u64 v[142:143], s[14:15], 0, v[130:131]
	s_add_i32 m0, s54, 0x2000
	s_nop 0
	global_load_lds_dwordx4 v[142:143], off
	v_lshl_add_u64 v[142:143], v[232:233], 0, s[10:11]
	s_mov_b32 m0, s63
	s_nop 0
	global_load_lds_dwordx4 v[142:143], off
	v_lshl_add_u64 v[142:143], v[234:235], 0, s[10:11]
	s_mov_b32 m0, s64
	s_nop 0
	global_load_lds_dwordx4 v[142:143], off
	s_waitcnt vmcnt(8)
	s_waitcnt lgkmcnt(0)
	s_setprio 1
	s_barrier
	v_mfma_f32_16x16x32_bf16 v[62:65], v[150:153], v[182:185], v[62:65]
	v_mfma_f32_16x16x32_bf16 v[58:61], v[158:161], v[182:185], v[58:61]
	v_mfma_f32_16x16x32_bf16 v[46:49], v[150:153], v[190:193], v[46:49]
	v_mfma_f32_16x16x32_bf16 v[42:45], v[158:161], v[190:193], v[42:45]
	v_mfma_f32_16x16x32_bf16 v[30:33], v[150:153], v[206:209], v[30:33]
	v_mfma_f32_16x16x32_bf16 v[26:29], v[158:161], v[206:209], v[26:29]
	v_mfma_f32_16x16x32_bf16 v[14:17], v[150:153], v[214:217], v[14:17]
	v_mfma_f32_16x16x32_bf16 v[10:13], v[158:161], v[214:217], v[10:13]
	v_mfma_f32_16x16x32_bf16 v[62:65], v[154:157], v[186:189], v[62:65]
	v_mfma_f32_16x16x32_bf16 v[58:61], v[162:165], v[186:189], v[58:61]
	v_mfma_f32_16x16x32_bf16 v[46:49], v[154:157], v[202:205], v[46:49]
	v_mfma_f32_16x16x32_bf16 v[42:45], v[162:165], v[202:205], v[42:45]
	v_mfma_f32_16x16x32_bf16 v[30:33], v[154:157], v[210:213], v[30:33]
	v_mfma_f32_16x16x32_bf16 v[26:29], v[162:165], v[210:213], v[26:29]
	v_mfma_f32_16x16x32_bf16 v[14:17], v[154:157], v[218:221], v[14:17]
	v_mfma_f32_16x16x32_bf16 v[10:13], v[162:165], v[218:221], v[10:13]
	v_mfma_f32_16x16x32_bf16 v[54:57], v[166:169], v[182:185], v[54:57]
	v_mfma_f32_16x16x32_bf16 v[50:53], v[174:177], v[182:185], v[50:53]
	v_mfma_f32_16x16x32_bf16 v[38:41], v[166:169], v[190:193], v[38:41]
	v_mfma_f32_16x16x32_bf16 v[34:37], v[174:177], v[190:193], v[34:37]
	v_mfma_f32_16x16x32_bf16 v[22:25], v[166:169], v[206:209], v[22:25]
	v_mfma_f32_16x16x32_bf16 v[18:21], v[174:177], v[206:209], v[18:21]
	v_mfma_f32_16x16x32_bf16 v[6:9], v[166:169], v[214:217], v[6:9]
	v_mfma_f32_16x16x32_bf16 v[2:5], v[174:177], v[214:217], v[2:5]
	v_mfma_f32_16x16x32_bf16 v[54:57], v[170:173], v[186:189], v[54:57]
	v_mfma_f32_16x16x32_bf16 v[50:53], v[178:181], v[186:189], v[50:53]
	v_mfma_f32_16x16x32_bf16 v[38:41], v[170:173], v[202:205], v[38:41]
	v_mfma_f32_16x16x32_bf16 v[34:37], v[178:181], v[202:205], v[34:37]
	v_mfma_f32_16x16x32_bf16 v[22:25], v[170:173], v[210:213], v[22:25]
	v_mfma_f32_16x16x32_bf16 v[18:21], v[178:181], v[210:213], v[18:21]
	v_mfma_f32_16x16x32_bf16 v[6:9], v[170:173], v[218:221], v[6:9]
	v_mfma_f32_16x16x32_bf16 v[2:5], v[178:181], v[218:221], v[2:5]
	s_barrier
	s_setprio 0
	s_add_i32 s49, s49, 2
	s_add_u32 s37, s37, 0x100
	s_addc_u32 s47, s47, 0
	s_add_u32 s12, s12, 0x100
	s_addc_u32 s13, s13, 0
	s_cmp_gt_u32 s49, 13
	s_cbranch_scc0 .LBB0_561
	s_and_b64 vcc, exec, s[44:45]
	s_cbranch_vccz .LBB0_564
	s_barrier

.LBB0_626:
	s_add_u32 s14, s12, 0xfff00080
	s_addc_u32 s15, s13, -1
	s_add_i32 s70, 0, 0x10000
	s_cmp_eq_u32 s53, 60
	s_cselect_b32 s59, s28, s15
	s_cselect_b32 s58, s29, s14
	s_cselect_b32 s15, s33, s51
	s_cselect_b32 s14, s36, s37
	s_add_i32 s72, 0, 0x14000
	v_add_u32_e32 v134, s70, v183
	v_add_u32_e32 v168, s72, v183
	ds_read_b128 v[114:117], v134
	ds_read_b128 v[118:121], v134 offset:1024
	ds_read_b128 v[122:125], v134 offset:2048
	ds_read_b128 v[134:137], v134 offset:3072
	ds_read_b128 v[146:149], v168
	ds_read_b128 v[150:153], v168 offset:1024
	ds_read_b128 v[164:167], v168 offset:2048
	ds_read_b128 v[168:171], v168 offset:3072
	v_lshl_add_u64 v[180:181], s[12:13], 0, v[162:163]
	s_add_i32 m0, s63, 0xc000
	ds_read_b128 v[172:175], v185
	ds_read_b128 v[176:179], v185 offset:1024
	ds_read_b128 v[186:189], v185 offset:2048
	ds_read_b128 v[190:193], v185 offset:3072
	ds_read_b128 v[202:205], v185 offset:4096
	ds_read_b128 v[206:209], v185 offset:5120
	ds_read_b128 v[210:213], v185 offset:6144
	ds_read_b128 v[214:217], v185 offset:7168
	global_load_lds_dwordx4 v[180:181], off
	v_lshl_add_u64 v[180:181], s[12:13], 0, v[160:161]
	s_add_i32 m0, s63, 0xe000
	s_nop 0
	global_load_lds_dwordx4 v[180:181], off
	s_waitcnt vmcnt(8)
	s_waitcnt lgkmcnt(0)
	s_setprio 1
	s_barrier
	v_mfma_f32_16x16x32_bf16 v[142:145], v[114:117], v[172:175], v[142:145]
	v_mfma_f32_16x16x32_bf16 v[138:141], v[122:125], v[172:175], v[138:141]
	v_mfma_f32_16x16x32_bf16 v[110:113], v[114:117], v[186:189], v[110:113]
	v_mfma_f32_16x16x32_bf16 v[106:109], v[122:125], v[186:189], v[106:109]
	v_mfma_f32_16x16x32_bf16 v[94:97], v[114:117], v[202:205], v[94:97]
	v_mfma_f32_16x16x32_bf16 v[90:93], v[122:125], v[202:205], v[90:93]
	v_mfma_f32_16x16x32_bf16 v[78:81], v[114:117], v[210:213], v[78:81]
	v_mfma_f32_16x16x32_bf16 v[74:77], v[122:125], v[210:213], v[74:77]
	v_mfma_f32_16x16x32_bf16 v[142:145], v[118:121], v[176:179], v[142:145]
	v_mfma_f32_16x16x32_bf16 v[138:141], v[134:137], v[176:179], v[138:141]
	v_mfma_f32_16x16x32_bf16 v[110:113], v[118:121], v[190:193], v[110:113]
	v_mfma_f32_16x16x32_bf16 v[106:109], v[134:137], v[190:193], v[106:109]
	v_mfma_f32_16x16x32_bf16 v[94:97], v[118:121], v[206:209], v[94:97]
	v_mfma_f32_16x16x32_bf16 v[90:93], v[134:137], v[206:209], v[90:93]
	v_mfma_f32_16x16x32_bf16 v[78:81], v[118:121], v[214:217], v[78:81]
	v_mfma_f32_16x16x32_bf16 v[74:77], v[134:137], v[214:217], v[74:77]
	v_mfma_f32_16x16x32_bf16 v[130:133], v[146:149], v[172:175], v[130:133]
	v_mfma_f32_16x16x32_bf16 v[126:129], v[164:167], v[172:175], v[126:129]
	v_mfma_f32_16x16x32_bf16 v[102:105], v[146:149], v[186:189], v[102:105]
	v_mfma_f32_16x16x32_bf16 v[98:101], v[164:167], v[186:189], v[98:101]
	v_mfma_f32_16x16x32_bf16 v[86:89], v[146:149], v[202:205], v[86:89]
	v_mfma_f32_16x16x32_bf16 v[82:85], v[164:167], v[202:205], v[82:85]
	v_mfma_f32_16x16x32_bf16 v[70:73], v[146:149], v[210:213], v[70:73]
	v_mfma_f32_16x16x32_bf16 v[66:69], v[164:167], v[210:213], v[66:69]
	v_mfma_f32_16x16x32_bf16 v[130:133], v[150:153], v[176:179], v[130:133]
	v_mfma_f32_16x16x32_bf16 v[126:129], v[168:171], v[176:179], v[126:129]
	v_mfma_f32_16x16x32_bf16 v[102:105], v[150:153], v[190:193], v[102:105]
	v_mfma_f32_16x16x32_bf16 v[98:101], v[168:171], v[190:193], v[98:101]
	v_mfma_f32_16x16x32_bf16 v[86:89], v[150:153], v[206:209], v[86:89]
	v_mfma_f32_16x16x32_bf16 v[82:85], v[168:171], v[206:209], v[82:85]
	v_mfma_f32_16x16x32_bf16 v[70:73], v[150:153], v[214:217], v[70:73]
	v_mfma_f32_16x16x32_bf16 v[66:69], v[168:171], v[214:217], v[66:69]
	s_barrier
	s_setprio 0
	s_add_i32 s70, s70, s62
	v_lshl_add_u64 v[180:181], s[14:15], 0, v[0:1]
	s_mov_b32 m0, s70
	ds_read_b128 v[172:175], v185 offset:16384
	ds_read_b128 v[176:179], v185 offset:17408
	ds_read_b128 v[186:189], v185 offset:18432
	ds_read_b128 v[190:193], v185 offset:19456
	ds_read_b128 v[202:205], v185 offset:20480
	ds_read_b128 v[206:209], v185 offset:21504
	ds_read_b128 v[210:213], v185 offset:22528
	ds_read_b128 v[214:217], v185 offset:23552
	global_load_lds_dwordx4 v[180:181], off
	s_add_i32 m0, s70, 0x2000
	s_add_u32 s70, s14, 0x100000
	v_lshl_add_u64 v[218:219], s[14:15], 0, v[154:155]
	s_addc_u32 s71, s15, 0
	s_add_i32 s72, s72, s62
	global_load_lds_dwordx4 v[218:219], off
	v_lshl_add_u64 v[220:221], s[70:71], 0, v[0:1]
	s_mov_b32 m0, s72
	v_lshl_add_u64 v[222:223], s[58:59], 0, v[156:157]
	global_load_lds_dwordx4 v[220:221], off
	v_lshl_add_u64 v[220:221], s[70:71], 0, v[154:155]
	s_add_i32 m0, s72, 0x2000
	s_nop 0
	global_load_lds_dwordx4 v[220:221], off
	v_lshl_add_u64 v[220:221], s[58:59], 0, v[158:159]
	s_mov_b32 m0, s63
	s_nop 0
	global_load_lds_dwordx4 v[220:221], off
	s_mov_b32 m0, s64
	s_nop 0
	global_load_lds_dwordx4 v[222:223], off
	s_waitcnt vmcnt(8)
	s_waitcnt lgkmcnt(0)
	s_setprio 1
	s_barrier
	v_mfma_f32_16x16x32_bf16 v[62:65], v[114:117], v[172:175], v[62:65]
	v_mfma_f32_16x16x32_bf16 v[58:61], v[122:125], v[172:175], v[58:61]
	v_mfma_f32_16x16x32_bf16 v[46:49], v[114:117], v[186:189], v[46:49]
	v_mfma_f32_16x16x32_bf16 v[42:45], v[122:125], v[186:189], v[42:45]
	v_mfma_f32_16x16x32_bf16 v[30:33], v[114:117], v[202:205], v[30:33]
	v_mfma_f32_16x16x32_bf16 v[26:29], v[122:125], v[202:205], v[26:29]
	v_mfma_f32_16x16x32_bf16 v[14:17], v[114:117], v[210:213], v[14:17]
	v_mfma_f32_16x16x32_bf16 v[10:13], v[122:125], v[210:213], v[10:13]
	v_mfma_f32_16x16x32_bf16 v[62:65], v[118:121], v[176:179], v[62:65]
	v_mfma_f32_16x16x32_bf16 v[58:61], v[134:137], v[176:179], v[58:61]
	v_mfma_f32_16x16x32_bf16 v[46:49], v[118:121], v[190:193], v[46:49]
	v_mfma_f32_16x16x32_bf16 v[42:45], v[134:137], v[190:193], v[42:45]
	v_mfma_f32_16x16x32_bf16 v[30:33], v[118:121], v[206:209], v[30:33]
	v_mfma_f32_16x16x32_bf16 v[26:29], v[134:137], v[206:209], v[26:29]
	v_mfma_f32_16x16x32_bf16 v[14:17], v[118:121], v[214:217], v[14:17]
	v_mfma_f32_16x16x32_bf16 v[10:13], v[134:137], v[214:217], v[10:13]
	v_mfma_f32_16x16x32_bf16 v[54:57], v[146:149], v[172:175], v[54:57]
	v_mfma_f32_16x16x32_bf16 v[50:53], v[164:167], v[172:175], v[50:53]
	v_mfma_f32_16x16x32_bf16 v[38:41], v[146:149], v[186:189], v[38:41]
	v_mfma_f32_16x16x32_bf16 v[34:37], v[164:167], v[186:189], v[34:37]
	v_mfma_f32_16x16x32_bf16 v[22:25], v[146:149], v[202:205], v[22:25]
	v_mfma_f32_16x16x32_bf16 v[18:21], v[164:167], v[202:205], v[18:21]
	v_mfma_f32_16x16x32_bf16 v[6:9], v[146:149], v[210:213], v[6:9]
	v_mfma_f32_16x16x32_bf16 v[2:5], v[164:167], v[210:213], v[2:5]
	v_mfma_f32_16x16x32_bf16 v[54:57], v[150:153], v[176:179], v[54:57]
	v_mfma_f32_16x16x32_bf16 v[50:53], v[168:171], v[176:179], v[50:53]
	v_mfma_f32_16x16x32_bf16 v[38:41], v[150:153], v[190:193], v[38:41]
	v_mfma_f32_16x16x32_bf16 v[34:37], v[168:171], v[190:193], v[34:37]
	v_mfma_f32_16x16x32_bf16 v[22:25], v[150:153], v[206:209], v[22:25]
	v_mfma_f32_16x16x32_bf16 v[18:21], v[168:171], v[206:209], v[18:21]
	v_mfma_f32_16x16x32_bf16 v[6:9], v[150:153], v[214:217], v[6:9]
	v_mfma_f32_16x16x32_bf16 v[2:5], v[168:171], v[214:217], v[2:5]
	s_barrier
	s_setprio 0
	s_add_i32 s70, 0, 0x18000
	s_add_i32 s71, 0, 0x1c000
	v_add_u32_e32 v134, s70, v183
	v_add_u32_e32 v168, s71, v183
	ds_read_b128 v[114:117], v134
	ds_read_b128 v[118:121], v134 offset:1024
	ds_read_b128 v[122:125], v134 offset:2048
	ds_read_b128 v[134:137], v134 offset:3072
	ds_read_b128 v[146:149], v168
	ds_read_b128 v[150:153], v168 offset:1024
	ds_read_b128 v[164:167], v168 offset:2048
	ds_read_b128 v[168:171], v168 offset:3072
	s_add_u32 s58, s58, 0x100000
	s_addc_u32 s59, s59, 0
	s_mov_b32 m0, s65
	v_lshl_add_u64 v[232:233], s[58:59], 0, v[158:159]
	ds_read_b128 v[172:175], v185 offset:32768
	ds_read_b128 v[176:179], v185 offset:33792
	ds_read_b128 v[186:189], v185 offset:34816
	ds_read_b128 v[190:193], v185 offset:35840
	ds_read_b128 v[202:205], v185 offset:36864
	ds_read_b128 v[206:209], v185 offset:37888
	ds_read_b128 v[210:213], v185 offset:38912
	ds_read_b128 v[214:217], v185 offset:39936
	global_load_lds_dwordx4 v[232:233], off
	v_lshl_add_u64 v[232:233], s[58:59], 0, v[156:157]
	s_mov_b32 m0, s66
	s_nop 0
	global_load_lds_dwordx4 v[232:233], off
	s_waitcnt vmcnt(8)
	s_waitcnt lgkmcnt(0)
	s_setprio 1
	s_barrier
	v_mfma_f32_16x16x32_bf16 v[142:145], v[114:117], v[172:175], v[142:145]
	v_mfma_f32_16x16x32_bf16 v[138:141], v[122:125], v[172:175], v[138:141]
	v_mfma_f32_16x16x32_bf16 v[110:113], v[114:117], v[186:189], v[110:113]
	v_mfma_f32_16x16x32_bf16 v[106:109], v[122:125], v[186:189], v[106:109]
	v_mfma_f32_16x16x32_bf16 v[94:97], v[114:117], v[202:205], v[94:97]
	v_mfma_f32_16x16x32_bf16 v[90:93], v[122:125], v[202:205], v[90:93]
	v_mfma_f32_16x16x32_bf16 v[78:81], v[114:117], v[210:213], v[78:81]
	v_mfma_f32_16x16x32_bf16 v[74:77], v[122:125], v[210:213], v[74:77]
	v_mfma_f32_16x16x32_bf16 v[142:145], v[118:121], v[176:179], v[142:145]
	v_mfma_f32_16x16x32_bf16 v[138:141], v[134:137], v[176:179], v[138:141]
	v_mfma_f32_16x16x32_bf16 v[110:113], v[118:121], v[190:193], v[110:113]
	v_mfma_f32_16x16x32_bf16 v[106:109], v[134:137], v[190:193], v[106:109]
	v_mfma_f32_16x16x32_bf16 v[94:97], v[118:121], v[206:209], v[94:97]
	v_mfma_f32_16x16x32_bf16 v[90:93], v[134:137], v[206:209], v[90:93]
	v_mfma_f32_16x16x32_bf16 v[78:81], v[118:121], v[214:217], v[78:81]
	v_mfma_f32_16x16x32_bf16 v[74:77], v[134:137], v[214:217], v[74:77]
	v_mfma_f32_16x16x32_bf16 v[130:133], v[146:149], v[172:175], v[130:133]
	v_mfma_f32_16x16x32_bf16 v[126:129], v[164:167], v[172:175], v[126:129]
	v_mfma_f32_16x16x32_bf16 v[102:105], v[146:149], v[186:189], v[102:105]
	v_mfma_f32_16x16x32_bf16 v[98:101], v[164:167], v[186:189], v[98:101]
	v_mfma_f32_16x16x32_bf16 v[86:89], v[146:149], v[202:205], v[86:89]
	v_mfma_f32_16x16x32_bf16 v[82:85], v[164:167], v[202:205], v[82:85]
	v_mfma_f32_16x16x32_bf16 v[70:73], v[146:149], v[210:213], v[70:73]
	v_mfma_f32_16x16x32_bf16 v[66:69], v[164:167], v[210:213], v[66:69]
	v_mfma_f32_16x16x32_bf16 v[130:133], v[150:153], v[176:179], v[130:133]
	v_mfma_f32_16x16x32_bf16 v[126:129], v[168:171], v[176:179], v[126:129]
	v_mfma_f32_16x16x32_bf16 v[102:105], v[150:153], v[190:193], v[102:105]
	v_mfma_f32_16x16x32_bf16 v[98:101], v[168:171], v[190:193], v[98:101]
	v_mfma_f32_16x16x32_bf16 v[86:89], v[150:153], v[206:209], v[86:89]
	v_mfma_f32_16x16x32_bf16 v[82:85], v[168:171], v[206:209], v[82:85]
	v_mfma_f32_16x16x32_bf16 v[70:73], v[150:153], v[214:217], v[70:73]
	v_mfma_f32_16x16x32_bf16 v[66:69], v[168:171], v[214:217], v[66:69]
	s_barrier
	s_setprio 0
	s_add_i32 s58, s70, s62
	v_lshl_add_u64 v[180:181], v[180:181], 0, s[10:11]
	s_mov_b32 m0, s58
	ds_read_b128 v[172:175], v185 offset:49152
	ds_read_b128 v[176:179], v185 offset:50176
	ds_read_b128 v[186:189], v185 offset:51200
	ds_read_b128 v[190:193], v185 offset:52224
	ds_read_b128 v[202:205], v185 offset:53248
	ds_read_b128 v[206:209], v185 offset:54272
	ds_read_b128 v[210:213], v185 offset:55296
	ds_read_b128 v[214:217], v185 offset:56320
	global_load_lds_dwordx4 v[180:181], off
	s_add_i32 m0, s58, 0x2000
	s_add_u32 s14, s14, 0x100080
	v_lshl_add_u64 v[180:181], v[218:219], 0, s[10:11]
	s_addc_u32 s15, s15, 0
	s_add_i32 s58, s71, s62
	global_load_lds_dwordx4 v[180:181], off
	v_lshl_add_u64 v[180:181], s[14:15], 0, v[0:1]
	s_mov_b32 m0, s58
	s_nop 0
	global_load_lds_dwordx4 v[180:181], off
	v_lshl_add_u64 v[180:181], s[14:15], 0, v[154:155]
	s_add_i32 m0, s58, 0x2000
	s_nop 0
	global_load_lds_dwordx4 v[180:181], off
	v_lshl_add_u64 v[180:181], v[220:221], 0, s[10:11]
	s_mov_b32 m0, s67
	s_nop 0
	global_load_lds_dwordx4 v[180:181], off
	v_lshl_add_u64 v[180:181], v[222:223], 0, s[10:11]
	s_mov_b32 m0, s68
	s_nop 0
	global_load_lds_dwordx4 v[180:181], off
	s_waitcnt vmcnt(8)
	s_waitcnt lgkmcnt(0)
	s_setprio 1
	s_barrier
	v_mfma_f32_16x16x32_bf16 v[62:65], v[114:117], v[172:175], v[62:65]
	v_mfma_f32_16x16x32_bf16 v[58:61], v[122:125], v[172:175], v[58:61]
	v_mfma_f32_16x16x32_bf16 v[46:49], v[114:117], v[186:189], v[46:49]
	v_mfma_f32_16x16x32_bf16 v[42:45], v[122:125], v[186:189], v[42:45]
	v_mfma_f32_16x16x32_bf16 v[30:33], v[114:117], v[202:205], v[30:33]
	v_mfma_f32_16x16x32_bf16 v[26:29], v[122:125], v[202:205], v[26:29]
	v_mfma_f32_16x16x32_bf16 v[14:17], v[114:117], v[210:213], v[14:17]
	v_mfma_f32_16x16x32_bf16 v[10:13], v[122:125], v[210:213], v[10:13]
	v_mfma_f32_16x16x32_bf16 v[62:65], v[118:121], v[176:179], v[62:65]
	v_mfma_f32_16x16x32_bf16 v[58:61], v[134:137], v[176:179], v[58:61]
	v_mfma_f32_16x16x32_bf16 v[46:49], v[118:121], v[190:193], v[46:49]
	v_mfma_f32_16x16x32_bf16 v[42:45], v[134:137], v[190:193], v[42:45]
	v_mfma_f32_16x16x32_bf16 v[30:33], v[118:121], v[206:209], v[30:33]
	v_mfma_f32_16x16x32_bf16 v[26:29], v[134:137], v[206:209], v[26:29]
	v_mfma_f32_16x16x32_bf16 v[14:17], v[118:121], v[214:217], v[14:17]
	v_mfma_f32_16x16x32_bf16 v[10:13], v[134:137], v[214:217], v[10:13]
	v_mfma_f32_16x16x32_bf16 v[54:57], v[146:149], v[172:175], v[54:57]
	v_mfma_f32_16x16x32_bf16 v[50:53], v[164:167], v[172:175], v[50:53]
	v_mfma_f32_16x16x32_bf16 v[38:41], v[146:149], v[186:189], v[38:41]
	v_mfma_f32_16x16x32_bf16 v[34:37], v[164:167], v[186:189], v[34:37]
	v_mfma_f32_16x16x32_bf16 v[22:25], v[146:149], v[202:205], v[22:25]
	v_mfma_f32_16x16x32_bf16 v[18:21], v[164:167], v[202:205], v[18:21]
	v_mfma_f32_16x16x32_bf16 v[6:9], v[146:149], v[210:213], v[6:9]
	v_mfma_f32_16x16x32_bf16 v[2:5], v[164:167], v[210:213], v[2:5]
	v_mfma_f32_16x16x32_bf16 v[54:57], v[150:153], v[176:179], v[54:57]
	v_mfma_f32_16x16x32_bf16 v[50:53], v[168:171], v[176:179], v[50:53]
	v_mfma_f32_16x16x32_bf16 v[38:41], v[150:153], v[190:193], v[38:41]
	v_mfma_f32_16x16x32_bf16 v[34:37], v[168:171], v[190:193], v[34:37]
	v_mfma_f32_16x16x32_bf16 v[22:25], v[150:153], v[206:209], v[22:25]
	v_mfma_f32_16x16x32_bf16 v[18:21], v[168:171], v[206:209], v[18:21]
	v_mfma_f32_16x16x32_bf16 v[6:9], v[150:153], v[214:217], v[6:9]
	v_mfma_f32_16x16x32_bf16 v[2:5], v[168:171], v[214:217], v[2:5]
	s_barrier
	s_setprio 0
	s_add_i32 s53, s53, 2
	s_add_u32 s37, s37, 0x100
	s_addc_u32 s51, s51, 0
	s_add_u32 s12, s12, 0x100
	s_addc_u32 s13, s13, 0
	s_cmp_gt_u32 s53, 61
	s_cbranch_scc0 .LBB0_626
	s_and_b64 vcc, exec, s[48:49]
	s_cbranch_vccz .LBB0_629
	s_barrier

.LBB0_711:
	s_add_i32 s29, s28, 2
	s_add_u32 s33, s14, 0x80
	s_addc_u32 s54, s15, 0
	s_add_i32 s72, 0, 0x10000
	s_cmp_eq_u32 s66, s28
	s_cselect_b32 s55, s5, s54
	s_cselect_b32 s54, s4, s33
	s_cselect_b32 s71, s13, s21
	s_cselect_b32 s70, s12, s20
	s_add_i32 s28, 0, 0x14000
	v_add_u32_e32 v156, s72, v141
	v_add_u32_e32 v172, s28, v141
	ds_read_b128 v[144:147], v156
	ds_read_b128 v[148:151], v156 offset:1024
	ds_read_b128 v[152:155], v156 offset:2048
	ds_read_b128 v[156:159], v156 offset:3072
	ds_read_b128 v[160:163], v172
	ds_read_b128 v[164:167], v172 offset:1024
	ds_read_b128 v[168:171], v172 offset:2048
	ds_read_b128 v[172:175], v172 offset:3072
	v_lshl_add_u64 v[192:193], s[14:15], 0, v[138:139]
	s_add_i32 m0, s59, 0xc000
	ds_read_b128 v[176:179], v143
	ds_read_b128 v[180:183], v143 offset:1024
	ds_read_b128 v[184:187], v143 offset:2048
	ds_read_b128 v[188:191], v143 offset:3072
	ds_read_b128 v[202:205], v143 offset:4096
	ds_read_b128 v[206:209], v143 offset:5120
	ds_read_b128 v[210:213], v143 offset:6144
	ds_read_b128 v[214:217], v143 offset:7168
	global_load_lds_dwordx4 v[192:193], off
	v_lshl_add_u64 v[192:193], s[14:15], 0, v[136:137]
	s_add_i32 m0, s59, 0xe000
	s_nop 0
	global_load_lds_dwordx4 v[192:193], off
	s_waitcnt vmcnt(8)
	s_waitcnt lgkmcnt(0)
	s_setprio 1
	s_barrier
	v_mfma_f32_16x16x32_bf16 v[122:125], v[144:147], v[176:179], v[122:125]
	v_mfma_f32_16x16x32_bf16 v[126:129], v[152:155], v[176:179], v[126:129]
	v_mfma_f32_16x16x32_bf16 v[110:113], v[144:147], v[184:187], v[110:113]
	v_mfma_f32_16x16x32_bf16 v[106:109], v[152:155], v[184:187], v[106:109]
	v_mfma_f32_16x16x32_bf16 v[94:97], v[144:147], v[202:205], v[94:97]
	v_mfma_f32_16x16x32_bf16 v[90:93], v[152:155], v[202:205], v[90:93]
	v_mfma_f32_16x16x32_bf16 v[78:81], v[144:147], v[210:213], v[78:81]
	v_mfma_f32_16x16x32_bf16 v[74:77], v[152:155], v[210:213], v[74:77]
	v_mfma_f32_16x16x32_bf16 v[122:125], v[148:151], v[180:183], v[122:125]
	v_mfma_f32_16x16x32_bf16 v[126:129], v[156:159], v[180:183], v[126:129]
	v_mfma_f32_16x16x32_bf16 v[110:113], v[148:151], v[188:191], v[110:113]
	v_mfma_f32_16x16x32_bf16 v[106:109], v[156:159], v[188:191], v[106:109]
	v_mfma_f32_16x16x32_bf16 v[94:97], v[148:151], v[206:209], v[94:97]
	v_mfma_f32_16x16x32_bf16 v[90:93], v[156:159], v[206:209], v[90:93]
	v_mfma_f32_16x16x32_bf16 v[78:81], v[148:151], v[214:217], v[78:81]
	v_mfma_f32_16x16x32_bf16 v[74:77], v[156:159], v[214:217], v[74:77]
	v_mfma_f32_16x16x32_bf16 v[118:121], v[160:163], v[176:179], v[118:121]
	v_mfma_f32_16x16x32_bf16 v[114:117], v[168:171], v[176:179], v[114:117]
	v_mfma_f32_16x16x32_bf16 v[102:105], v[160:163], v[184:187], v[102:105]
	v_mfma_f32_16x16x32_bf16 v[98:101], v[168:171], v[184:187], v[98:101]
	v_mfma_f32_16x16x32_bf16 v[86:89], v[160:163], v[202:205], v[86:89]
	v_mfma_f32_16x16x32_bf16 v[82:85], v[168:171], v[202:205], v[82:85]
	v_mfma_f32_16x16x32_bf16 v[70:73], v[160:163], v[210:213], v[70:73]
	v_mfma_f32_16x16x32_bf16 v[66:69], v[168:171], v[210:213], v[66:69]
	v_mfma_f32_16x16x32_bf16 v[118:121], v[164:167], v[180:183], v[118:121]
	v_mfma_f32_16x16x32_bf16 v[114:117], v[172:175], v[180:183], v[114:117]
	v_mfma_f32_16x16x32_bf16 v[102:105], v[164:167], v[188:191], v[102:105]
	v_mfma_f32_16x16x32_bf16 v[98:101], v[172:175], v[188:191], v[98:101]
	v_mfma_f32_16x16x32_bf16 v[86:89], v[164:167], v[206:209], v[86:89]
	v_mfma_f32_16x16x32_bf16 v[82:85], v[172:175], v[206:209], v[82:85]
	v_mfma_f32_16x16x32_bf16 v[70:73], v[164:167], v[214:217], v[70:73]
	v_mfma_f32_16x16x32_bf16 v[66:69], v[172:175], v[214:217], v[66:69]
	s_barrier
	s_setprio 0
	s_add_i32 s33, s72, s58
	v_lshl_add_u64 v[192:193], s[70:71], 0, v[0:1]
	s_mov_b32 m0, s33
	ds_read_b128 v[176:179], v143 offset:16384
	ds_read_b128 v[180:183], v143 offset:17408
	ds_read_b128 v[184:187], v143 offset:18432
	ds_read_b128 v[188:191], v143 offset:19456
	ds_read_b128 v[202:205], v143 offset:20480
	ds_read_b128 v[206:209], v143 offset:21504
	ds_read_b128 v[210:213], v143 offset:22528
	ds_read_b128 v[214:217], v143 offset:23552
	global_load_lds_dwordx4 v[192:193], off
	s_add_i32 m0, s33, 0x2000
	v_lshl_add_u64 v[218:219], s[70:71], 0, v[130:131]
	s_add_u32 s70, s70, s42
	s_addc_u32 s71, s71, s43
	s_add_i32 s28, s28, s58
	global_load_lds_dwordx4 v[218:219], off
	v_lshl_add_u64 v[220:221], s[70:71], 0, v[0:1]
	s_mov_b32 m0, s28
	v_lshl_add_u64 v[222:223], s[70:71], 0, v[130:131]
	global_load_lds_dwordx4 v[220:221], off
	s_add_i32 m0, s28, 0x2000
	v_lshl_add_u64 v[232:233], s[54:55], 0, v[134:135]
	global_load_lds_dwordx4 v[222:223], off
	s_mov_b32 m0, s59
	v_lshl_add_u64 v[234:235], s[54:55], 0, v[132:133]
	global_load_lds_dwordx4 v[232:233], off
	s_mov_b32 m0, s60
	s_nop 0
	global_load_lds_dwordx4 v[234:235], off
	s_waitcnt vmcnt(8)
	s_waitcnt lgkmcnt(0)
	s_setprio 1
	s_barrier
	v_mfma_f32_16x16x32_bf16 v[62:65], v[144:147], v[176:179], v[62:65]
	v_mfma_f32_16x16x32_bf16 v[58:61], v[152:155], v[176:179], v[58:61]
	v_mfma_f32_16x16x32_bf16 v[46:49], v[144:147], v[184:187], v[46:49]
	v_mfma_f32_16x16x32_bf16 v[42:45], v[152:155], v[184:187], v[42:45]
	v_mfma_f32_16x16x32_bf16 v[30:33], v[144:147], v[202:205], v[30:33]
	v_mfma_f32_16x16x32_bf16 v[26:29], v[152:155], v[202:205], v[26:29]
	v_mfma_f32_16x16x32_bf16 v[14:17], v[144:147], v[210:213], v[14:17]
	v_mfma_f32_16x16x32_bf16 v[10:13], v[152:155], v[210:213], v[10:13]
	v_mfma_f32_16x16x32_bf16 v[62:65], v[148:151], v[180:183], v[62:65]
	v_mfma_f32_16x16x32_bf16 v[58:61], v[156:159], v[180:183], v[58:61]
	v_mfma_f32_16x16x32_bf16 v[46:49], v[148:151], v[188:191], v[46:49]
	v_mfma_f32_16x16x32_bf16 v[42:45], v[156:159], v[188:191], v[42:45]
	v_mfma_f32_16x16x32_bf16 v[30:33], v[148:151], v[206:209], v[30:33]
	v_mfma_f32_16x16x32_bf16 v[26:29], v[156:159], v[206:209], v[26:29]
	v_mfma_f32_16x16x32_bf16 v[14:17], v[148:151], v[214:217], v[14:17]
	v_mfma_f32_16x16x32_bf16 v[10:13], v[156:159], v[214:217], v[10:13]
	v_mfma_f32_16x16x32_bf16 v[54:57], v[160:163], v[176:179], v[54:57]
	v_mfma_f32_16x16x32_bf16 v[50:53], v[168:171], v[176:179], v[50:53]
	v_mfma_f32_16x16x32_bf16 v[38:41], v[160:163], v[184:187], v[38:41]
	v_mfma_f32_16x16x32_bf16 v[34:37], v[168:171], v[184:187], v[34:37]
	v_mfma_f32_16x16x32_bf16 v[22:25], v[160:163], v[202:205], v[22:25]
	v_mfma_f32_16x16x32_bf16 v[18:21], v[168:171], v[202:205], v[18:21]
	v_mfma_f32_16x16x32_bf16 v[6:9], v[160:163], v[210:213], v[6:9]
	v_mfma_f32_16x16x32_bf16 v[2:5], v[168:171], v[210:213], v[2:5]
	v_mfma_f32_16x16x32_bf16 v[54:57], v[164:167], v[180:183], v[54:57]
	v_mfma_f32_16x16x32_bf16 v[50:53], v[172:175], v[180:183], v[50:53]
	v_mfma_f32_16x16x32_bf16 v[38:41], v[164:167], v[188:191], v[38:41]
	v_mfma_f32_16x16x32_bf16 v[34:37], v[172:175], v[188:191], v[34:37]
	v_mfma_f32_16x16x32_bf16 v[22:25], v[164:167], v[206:209], v[22:25]
	v_mfma_f32_16x16x32_bf16 v[18:21], v[172:175], v[206:209], v[18:21]
	v_mfma_f32_16x16x32_bf16 v[6:9], v[164:167], v[214:217], v[6:9]
	v_mfma_f32_16x16x32_bf16 v[2:5], v[172:175], v[214:217], v[2:5]
	s_barrier
	s_setprio 0
	s_add_i32 s28, 0, 0x18000
	s_add_i32 s33, 0, 0x1c000
	v_add_u32_e32 v156, s28, v141
	v_add_u32_e32 v172, s33, v141
	ds_read_b128 v[144:147], v156
	ds_read_b128 v[148:151], v156 offset:1024
	ds_read_b128 v[152:155], v156 offset:2048
	ds_read_b128 v[156:159], v156 offset:3072
	ds_read_b128 v[160:163], v172
	ds_read_b128 v[164:167], v172 offset:1024
	ds_read_b128 v[168:171], v172 offset:2048
	ds_read_b128 v[172:175], v172 offset:3072
	s_add_u32 s54, s54, s42
	s_addc_u32 s55, s55, s43
	s_mov_b32 m0, s61
	v_lshl_add_u64 v[236:237], s[54:55], 0, v[134:135]
	ds_read_b128 v[176:179], v143 offset:32768
	ds_read_b128 v[180:183], v143 offset:33792
	ds_read_b128 v[184:187], v143 offset:34816
	ds_read_b128 v[188:191], v143 offset:35840
	ds_read_b128 v[202:205], v143 offset:36864
	ds_read_b128 v[206:209], v143 offset:37888
	ds_read_b128 v[210:213], v143 offset:38912
	ds_read_b128 v[214:217], v143 offset:39936
	global_load_lds_dwordx4 v[236:237], off
	v_lshl_add_u64 v[236:237], s[54:55], 0, v[132:133]
	s_mov_b32 m0, s62
	s_nop 0
	global_load_lds_dwordx4 v[236:237], off
	s_waitcnt vmcnt(8)
	s_waitcnt lgkmcnt(0)
	s_setprio 1
	s_barrier
	v_mfma_f32_16x16x32_bf16 v[122:125], v[144:147], v[176:179], v[122:125]
	v_mfma_f32_16x16x32_bf16 v[126:129], v[152:155], v[176:179], v[126:129]
	v_mfma_f32_16x16x32_bf16 v[110:113], v[144:147], v[184:187], v[110:113]
	v_mfma_f32_16x16x32_bf16 v[106:109], v[152:155], v[184:187], v[106:109]
	v_mfma_f32_16x16x32_bf16 v[94:97], v[144:147], v[202:205], v[94:97]
	v_mfma_f32_16x16x32_bf16 v[90:93], v[152:155], v[202:205], v[90:93]
	v_mfma_f32_16x16x32_bf16 v[78:81], v[144:147], v[210:213], v[78:81]
	v_mfma_f32_16x16x32_bf16 v[74:77], v[152:155], v[210:213], v[74:77]
	v_mfma_f32_16x16x32_bf16 v[122:125], v[148:151], v[180:183], v[122:125]
	v_mfma_f32_16x16x32_bf16 v[126:129], v[156:159], v[180:183], v[126:129]
	v_mfma_f32_16x16x32_bf16 v[110:113], v[148:151], v[188:191], v[110:113]
	v_mfma_f32_16x16x32_bf16 v[106:109], v[156:159], v[188:191], v[106:109]
	v_mfma_f32_16x16x32_bf16 v[94:97], v[148:151], v[206:209], v[94:97]
	v_mfma_f32_16x16x32_bf16 v[90:93], v[156:159], v[206:209], v[90:93]
	v_mfma_f32_16x16x32_bf16 v[78:81], v[148:151], v[214:217], v[78:81]
	v_mfma_f32_16x16x32_bf16 v[74:77], v[156:159], v[214:217], v[74:77]
	v_mfma_f32_16x16x32_bf16 v[118:121], v[160:163], v[176:179], v[118:121]
	v_mfma_f32_16x16x32_bf16 v[114:117], v[168:171], v[176:179], v[114:117]
	v_mfma_f32_16x16x32_bf16 v[102:105], v[160:163], v[184:187], v[102:105]
	v_mfma_f32_16x16x32_bf16 v[98:101], v[168:171], v[184:187], v[98:101]
	v_mfma_f32_16x16x32_bf16 v[86:89], v[160:163], v[202:205], v[86:89]
	v_mfma_f32_16x16x32_bf16 v[82:85], v[168:171], v[202:205], v[82:85]
	v_mfma_f32_16x16x32_bf16 v[70:73], v[160:163], v[210:213], v[70:73]
	v_mfma_f32_16x16x32_bf16 v[66:69], v[168:171], v[210:213], v[66:69]
	v_mfma_f32_16x16x32_bf16 v[118:121], v[164:167], v[180:183], v[118:121]
	v_mfma_f32_16x16x32_bf16 v[114:117], v[172:175], v[180:183], v[114:117]
	v_mfma_f32_16x16x32_bf16 v[102:105], v[164:167], v[188:191], v[102:105]
	v_mfma_f32_16x16x32_bf16 v[98:101], v[172:175], v[188:191], v[98:101]
	v_mfma_f32_16x16x32_bf16 v[86:89], v[164:167], v[206:209], v[86:89]
	v_mfma_f32_16x16x32_bf16 v[82:85], v[172:175], v[206:209], v[82:85]
	v_mfma_f32_16x16x32_bf16 v[70:73], v[164:167], v[214:217], v[70:73]
	v_mfma_f32_16x16x32_bf16 v[66:69], v[172:175], v[214:217], v[66:69]
	s_barrier
	s_setprio 0
	s_add_i32 s28, s28, s58
	v_lshl_add_u64 v[192:193], v[192:193], 0, s[10:11]
	s_mov_b32 m0, s28
	ds_read_b128 v[176:179], v143 offset:49152
	ds_read_b128 v[180:183], v143 offset:50176
	ds_read_b128 v[184:187], v143 offset:51200
	ds_read_b128 v[188:191], v143 offset:52224
	ds_read_b128 v[202:205], v143 offset:53248
	ds_read_b128 v[206:209], v143 offset:54272
	ds_read_b128 v[210:213], v143 offset:55296
	ds_read_b128 v[214:217], v143 offset:56320
	global_load_lds_dwordx4 v[192:193], off
	v_lshl_add_u64 v[192:193], v[218:219], 0, s[10:11]
	s_add_i32 m0, s28, 0x2000
	s_add_i32 s28, s33, s58
	global_load_lds_dwordx4 v[192:193], off
	v_lshl_add_u64 v[192:193], v[220:221], 0, s[10:11]
	s_mov_b32 m0, s28
	s_nop 0
	global_load_lds_dwordx4 v[192:193], off
	v_lshl_add_u64 v[192:193], v[222:223], 0, s[10:11]
	s_add_i32 m0, s28, 0x2000
	s_nop 0
	global_load_lds_dwordx4 v[192:193], off
	v_lshl_add_u64 v[192:193], v[232:233], 0, s[10:11]
	s_mov_b32 m0, s64
	s_nop 0
	global_load_lds_dwordx4 v[192:193], off
	v_lshl_add_u64 v[192:193], v[234:235], 0, s[10:11]
	s_mov_b32 m0, s65
	s_nop 0
	global_load_lds_dwordx4 v[192:193], off
	s_waitcnt vmcnt(8)
	s_waitcnt lgkmcnt(0)
	s_setprio 1
	s_barrier
	v_mfma_f32_16x16x32_bf16 v[62:65], v[144:147], v[176:179], v[62:65]
	v_mfma_f32_16x16x32_bf16 v[58:61], v[152:155], v[176:179], v[58:61]
	v_mfma_f32_16x16x32_bf16 v[46:49], v[144:147], v[184:187], v[46:49]
	v_mfma_f32_16x16x32_bf16 v[42:45], v[152:155], v[184:187], v[42:45]
	v_mfma_f32_16x16x32_bf16 v[30:33], v[144:147], v[202:205], v[30:33]
	v_mfma_f32_16x16x32_bf16 v[26:29], v[152:155], v[202:205], v[26:29]
	v_mfma_f32_16x16x32_bf16 v[14:17], v[144:147], v[210:213], v[14:17]
	v_mfma_f32_16x16x32_bf16 v[10:13], v[152:155], v[210:213], v[10:13]
	v_mfma_f32_16x16x32_bf16 v[62:65], v[148:151], v[180:183], v[62:65]
	v_mfma_f32_16x16x32_bf16 v[58:61], v[156:159], v[180:183], v[58:61]
	v_mfma_f32_16x16x32_bf16 v[46:49], v[148:151], v[188:191], v[46:49]
	v_mfma_f32_16x16x32_bf16 v[42:45], v[156:159], v[188:191], v[42:45]
	v_mfma_f32_16x16x32_bf16 v[30:33], v[148:151], v[206:209], v[30:33]
	v_mfma_f32_16x16x32_bf16 v[26:29], v[156:159], v[206:209], v[26:29]
	v_mfma_f32_16x16x32_bf16 v[14:17], v[148:151], v[214:217], v[14:17]
	v_mfma_f32_16x16x32_bf16 v[10:13], v[156:159], v[214:217], v[10:13]
	v_mfma_f32_16x16x32_bf16 v[54:57], v[160:163], v[176:179], v[54:57]
	v_mfma_f32_16x16x32_bf16 v[50:53], v[168:171], v[176:179], v[50:53]
	v_mfma_f32_16x16x32_bf16 v[38:41], v[160:163], v[184:187], v[38:41]
	v_mfma_f32_16x16x32_bf16 v[34:37], v[168:171], v[184:187], v[34:37]
	v_mfma_f32_16x16x32_bf16 v[22:25], v[160:163], v[202:205], v[22:25]
	v_mfma_f32_16x16x32_bf16 v[18:21], v[168:171], v[202:205], v[18:21]
	v_mfma_f32_16x16x32_bf16 v[6:9], v[160:163], v[210:213], v[6:9]
	v_mfma_f32_16x16x32_bf16 v[2:5], v[168:171], v[210:213], v[2:5]
	v_mfma_f32_16x16x32_bf16 v[54:57], v[164:167], v[180:183], v[54:57]
	v_mfma_f32_16x16x32_bf16 v[50:53], v[172:175], v[180:183], v[50:53]
	v_mfma_f32_16x16x32_bf16 v[38:41], v[164:167], v[188:191], v[38:41]
	v_mfma_f32_16x16x32_bf16 v[34:37], v[172:175], v[188:191], v[34:37]
	v_mfma_f32_16x16x32_bf16 v[22:25], v[164:167], v[206:209], v[22:25]
	v_mfma_f32_16x16x32_bf16 v[18:21], v[172:175], v[206:209], v[18:21]
	v_mfma_f32_16x16x32_bf16 v[6:9], v[164:167], v[214:217], v[6:9]
	v_mfma_f32_16x16x32_bf16 v[2:5], v[172:175], v[214:217], v[2:5]
	s_barrier
	s_setprio 0
	s_add_u32 s20, s20, 0x100
	s_addc_u32 s21, s21, 0
	s_add_u32 s14, s14, 0x100
	s_addc_u32 s15, s15, 0
	s_cmp_ge_i32 s29, s63
	s_mov_b32 s28, s29
	s_cbranch_scc0 .LBB0_711

.LBB0_731:
	s_add_u32 s37, s14, 0xfffc0080
	s_addc_u32 s51, s15, -1
	s_add_i32 s53, 0, 0x10000
	s_cmp_eq_u32 s36, 12
	s_cselect_b32 s63, s13, s51
	s_cselect_b32 s62, s20, s37
	s_cselect_b32 s61, s21, s33
	s_cselect_b32 s60, s28, s29
	s_add_i32 s37, 0, 0x14000
	v_add_u32_e32 v142, s53, v232
	v_add_u32_e32 v158, s37, v232
	ds_read_b128 v[126:129], v142
	ds_read_b128 v[134:137], v142 offset:1024
	ds_read_b128 v[138:141], v142 offset:2048
	ds_read_b128 v[142:145], v142 offset:3072
	ds_read_b128 v[146:149], v158
	ds_read_b128 v[150:153], v158 offset:1024
	ds_read_b128 v[154:157], v158 offset:2048
	ds_read_b128 v[158:161], v158 offset:3072
	v_lshl_add_u64 v[212:213], s[14:15], 0, v[210:211]
	s_add_i32 m0, s59, 0xc000
	ds_read_b128 v[162:165], v234
	ds_read_b128 v[166:169], v234 offset:1024
	ds_read_b128 v[170:173], v234 offset:2048
	ds_read_b128 v[174:177], v234 offset:3072
	ds_read_b128 v[178:181], v234 offset:4096
	ds_read_b128 v[182:185], v234 offset:5120
	ds_read_b128 v[186:189], v234 offset:6144
	ds_read_b128 v[190:193], v234 offset:7168
	global_load_lds_dwordx4 v[212:213], off
	v_lshl_add_u64 v[212:213], s[14:15], 0, v[208:209]
	s_add_i32 m0, s59, 0xe000
	s_nop 0
	global_load_lds_dwordx4 v[212:213], off
	s_waitcnt vmcnt(8)
	s_waitcnt lgkmcnt(0)
	s_setprio 1
	s_barrier
	v_mfma_f32_16x16x32_bf16 v[130:133], v[126:129], v[162:165], v[130:133]
	v_mfma_f32_16x16x32_bf16 v[122:125], v[138:141], v[162:165], v[122:125]
	v_mfma_f32_16x16x32_bf16 v[110:113], v[126:129], v[170:173], v[110:113]
	v_mfma_f32_16x16x32_bf16 v[106:109], v[138:141], v[170:173], v[106:109]
	v_mfma_f32_16x16x32_bf16 v[94:97], v[126:129], v[178:181], v[94:97]
	v_mfma_f32_16x16x32_bf16 v[90:93], v[138:141], v[178:181], v[90:93]
	v_mfma_f32_16x16x32_bf16 v[78:81], v[126:129], v[186:189], v[78:81]
	v_mfma_f32_16x16x32_bf16 v[74:77], v[138:141], v[186:189], v[74:77]
	v_mfma_f32_16x16x32_bf16 v[130:133], v[134:137], v[166:169], v[130:133]
	v_mfma_f32_16x16x32_bf16 v[122:125], v[142:145], v[166:169], v[122:125]
	v_mfma_f32_16x16x32_bf16 v[110:113], v[134:137], v[174:177], v[110:113]
	v_mfma_f32_16x16x32_bf16 v[106:109], v[142:145], v[174:177], v[106:109]
	v_mfma_f32_16x16x32_bf16 v[94:97], v[134:137], v[182:185], v[94:97]
	v_mfma_f32_16x16x32_bf16 v[90:93], v[142:145], v[182:185], v[90:93]
	v_mfma_f32_16x16x32_bf16 v[78:81], v[134:137], v[190:193], v[78:81]
	v_mfma_f32_16x16x32_bf16 v[74:77], v[142:145], v[190:193], v[74:77]
	v_mfma_f32_16x16x32_bf16 v[118:121], v[146:149], v[162:165], v[118:121]
	v_mfma_f32_16x16x32_bf16 v[114:117], v[154:157], v[162:165], v[114:117]
	v_mfma_f32_16x16x32_bf16 v[102:105], v[146:149], v[170:173], v[102:105]
	v_mfma_f32_16x16x32_bf16 v[98:101], v[154:157], v[170:173], v[98:101]
	v_mfma_f32_16x16x32_bf16 v[86:89], v[146:149], v[178:181], v[86:89]
	v_mfma_f32_16x16x32_bf16 v[82:85], v[154:157], v[178:181], v[82:85]
	v_mfma_f32_16x16x32_bf16 v[70:73], v[146:149], v[186:189], v[70:73]
	v_mfma_f32_16x16x32_bf16 v[66:69], v[154:157], v[186:189], v[66:69]
	v_mfma_f32_16x16x32_bf16 v[118:121], v[150:153], v[166:169], v[118:121]
	v_mfma_f32_16x16x32_bf16 v[114:117], v[158:161], v[166:169], v[114:117]
	v_mfma_f32_16x16x32_bf16 v[102:105], v[150:153], v[174:177], v[102:105]
	v_mfma_f32_16x16x32_bf16 v[98:101], v[158:161], v[174:177], v[98:101]
	v_mfma_f32_16x16x32_bf16 v[86:89], v[150:153], v[182:185], v[86:89]
	v_mfma_f32_16x16x32_bf16 v[82:85], v[158:161], v[182:185], v[82:85]
	v_mfma_f32_16x16x32_bf16 v[70:73], v[150:153], v[190:193], v[70:73]
	v_mfma_f32_16x16x32_bf16 v[66:69], v[158:161], v[190:193], v[66:69]
	s_barrier
	s_setprio 0
	s_add_i32 s51, s53, s66
	v_lshl_add_u64 v[212:213], s[60:61], 0, v[0:1]
	s_mov_b32 m0, s51
	ds_read_b128 v[162:165], v234 offset:16384
	ds_read_b128 v[166:169], v234 offset:17408
	ds_read_b128 v[170:173], v234 offset:18432
	ds_read_b128 v[174:177], v234 offset:19456
	ds_read_b128 v[178:181], v234 offset:20480
	ds_read_b128 v[182:185], v234 offset:21504
	ds_read_b128 v[186:189], v234 offset:22528
	ds_read_b128 v[190:193], v234 offset:23552
	global_load_lds_dwordx4 v[212:213], off
	s_add_i32 m0, s51, 0x2000
	s_add_u32 s74, s60, 0x40000
	v_lshl_add_u64 v[214:215], s[60:61], 0, v[202:203]
	s_addc_u32 s75, s61, 0
	s_add_i32 s37, s37, s66
	global_load_lds_dwordx4 v[214:215], off
	v_lshl_add_u64 v[216:217], s[74:75], 0, v[0:1]
	s_mov_b32 m0, s37
	v_lshl_add_u64 v[218:219], s[62:63], 0, v[204:205]
	global_load_lds_dwordx4 v[216:217], off
	v_lshl_add_u64 v[216:217], s[74:75], 0, v[202:203]
	s_add_i32 m0, s37, 0x2000
	s_nop 0
	global_load_lds_dwordx4 v[216:217], off
	v_lshl_add_u64 v[216:217], s[62:63], 0, v[206:207]
	s_mov_b32 m0, s59
	s_nop 0
	global_load_lds_dwordx4 v[216:217], off
	s_mov_b32 m0, s67
	s_nop 0
	global_load_lds_dwordx4 v[218:219], off
	s_waitcnt vmcnt(8)
	s_waitcnt lgkmcnt(0)
	s_setprio 1
	s_barrier
	v_mfma_f32_16x16x32_bf16 v[62:65], v[126:129], v[162:165], v[62:65]
	v_mfma_f32_16x16x32_bf16 v[58:61], v[138:141], v[162:165], v[58:61]
	v_mfma_f32_16x16x32_bf16 v[46:49], v[126:129], v[170:173], v[46:49]
	v_mfma_f32_16x16x32_bf16 v[42:45], v[138:141], v[170:173], v[42:45]
	v_mfma_f32_16x16x32_bf16 v[30:33], v[126:129], v[178:181], v[30:33]
	v_mfma_f32_16x16x32_bf16 v[26:29], v[138:141], v[178:181], v[26:29]
	v_mfma_f32_16x16x32_bf16 v[14:17], v[126:129], v[186:189], v[14:17]
	v_mfma_f32_16x16x32_bf16 v[10:13], v[138:141], v[186:189], v[10:13]
	v_mfma_f32_16x16x32_bf16 v[62:65], v[134:137], v[166:169], v[62:65]
	v_mfma_f32_16x16x32_bf16 v[58:61], v[142:145], v[166:169], v[58:61]
	v_mfma_f32_16x16x32_bf16 v[46:49], v[134:137], v[174:177], v[46:49]
	v_mfma_f32_16x16x32_bf16 v[42:45], v[142:145], v[174:177], v[42:45]
	v_mfma_f32_16x16x32_bf16 v[30:33], v[134:137], v[182:185], v[30:33]
	v_mfma_f32_16x16x32_bf16 v[26:29], v[142:145], v[182:185], v[26:29]
	v_mfma_f32_16x16x32_bf16 v[14:17], v[134:137], v[190:193], v[14:17]
	v_mfma_f32_16x16x32_bf16 v[10:13], v[142:145], v[190:193], v[10:13]
	v_mfma_f32_16x16x32_bf16 v[54:57], v[146:149], v[162:165], v[54:57]
	v_mfma_f32_16x16x32_bf16 v[50:53], v[154:157], v[162:165], v[50:53]
	v_mfma_f32_16x16x32_bf16 v[38:41], v[146:149], v[170:173], v[38:41]
	v_mfma_f32_16x16x32_bf16 v[34:37], v[154:157], v[170:173], v[34:37]
	v_mfma_f32_16x16x32_bf16 v[22:25], v[146:149], v[178:181], v[22:25]
	v_mfma_f32_16x16x32_bf16 v[18:21], v[154:157], v[178:181], v[18:21]
	v_mfma_f32_16x16x32_bf16 v[6:9], v[146:149], v[186:189], v[6:9]
	v_mfma_f32_16x16x32_bf16 v[2:5], v[154:157], v[186:189], v[2:5]
	v_mfma_f32_16x16x32_bf16 v[54:57], v[150:153], v[166:169], v[54:57]
	v_mfma_f32_16x16x32_bf16 v[50:53], v[158:161], v[166:169], v[50:53]
	v_mfma_f32_16x16x32_bf16 v[38:41], v[150:153], v[174:177], v[38:41]
	v_mfma_f32_16x16x32_bf16 v[34:37], v[158:161], v[174:177], v[34:37]
	v_mfma_f32_16x16x32_bf16 v[22:25], v[150:153], v[182:185], v[22:25]
	v_mfma_f32_16x16x32_bf16 v[18:21], v[158:161], v[182:185], v[18:21]
	v_mfma_f32_16x16x32_bf16 v[6:9], v[150:153], v[190:193], v[6:9]
	v_mfma_f32_16x16x32_bf16 v[2:5], v[158:161], v[190:193], v[2:5]
	s_barrier
	s_setprio 0
	s_add_i32 s37, 0, 0x18000
	s_add_i32 s51, 0, 0x1c000
	v_add_u32_e32 v142, s37, v232
	v_add_u32_e32 v158, s51, v232
	ds_read_b128 v[126:129], v142
	ds_read_b128 v[134:137], v142 offset:1024
	ds_read_b128 v[138:141], v142 offset:2048
	ds_read_b128 v[142:145], v142 offset:3072
	ds_read_b128 v[146:149], v158
	ds_read_b128 v[150:153], v158 offset:1024
	ds_read_b128 v[154:157], v158 offset:2048
	ds_read_b128 v[158:161], v158 offset:3072
	s_add_u32 s62, s62, 0x40000
	s_addc_u32 s63, s63, 0
	s_mov_b32 m0, s68
	v_lshl_add_u64 v[220:221], s[62:63], 0, v[206:207]
	ds_read_b128 v[162:165], v234 offset:32768
	ds_read_b128 v[166:169], v234 offset:33792
	ds_read_b128 v[170:173], v234 offset:34816
	ds_read_b128 v[174:177], v234 offset:35840
	ds_read_b128 v[178:181], v234 offset:36864
	ds_read_b128 v[182:185], v234 offset:37888
	ds_read_b128 v[186:189], v234 offset:38912
	ds_read_b128 v[190:193], v234 offset:39936
	global_load_lds_dwordx4 v[220:221], off
	v_lshl_add_u64 v[220:221], s[62:63], 0, v[204:205]
	s_mov_b32 m0, s69
	s_nop 0
	global_load_lds_dwordx4 v[220:221], off
	s_waitcnt vmcnt(8)
	s_waitcnt lgkmcnt(0)
	s_setprio 1
	s_barrier
	v_mfma_f32_16x16x32_bf16 v[130:133], v[126:129], v[162:165], v[130:133]
	v_mfma_f32_16x16x32_bf16 v[122:125], v[138:141], v[162:165], v[122:125]
	v_mfma_f32_16x16x32_bf16 v[110:113], v[126:129], v[170:173], v[110:113]
	v_mfma_f32_16x16x32_bf16 v[106:109], v[138:141], v[170:173], v[106:109]
	v_mfma_f32_16x16x32_bf16 v[94:97], v[126:129], v[178:181], v[94:97]
	v_mfma_f32_16x16x32_bf16 v[90:93], v[138:141], v[178:181], v[90:93]
	v_mfma_f32_16x16x32_bf16 v[78:81], v[126:129], v[186:189], v[78:81]
	v_mfma_f32_16x16x32_bf16 v[74:77], v[138:141], v[186:189], v[74:77]
	v_mfma_f32_16x16x32_bf16 v[130:133], v[134:137], v[166:169], v[130:133]
	v_mfma_f32_16x16x32_bf16 v[122:125], v[142:145], v[166:169], v[122:125]
	v_mfma_f32_16x16x32_bf16 v[110:113], v[134:137], v[174:177], v[110:113]
	v_mfma_f32_16x16x32_bf16 v[106:109], v[142:145], v[174:177], v[106:109]
	v_mfma_f32_16x16x32_bf16 v[94:97], v[134:137], v[182:185], v[94:97]
	v_mfma_f32_16x16x32_bf16 v[90:93], v[142:145], v[182:185], v[90:93]
	v_mfma_f32_16x16x32_bf16 v[78:81], v[134:137], v[190:193], v[78:81]
	v_mfma_f32_16x16x32_bf16 v[74:77], v[142:145], v[190:193], v[74:77]
	v_mfma_f32_16x16x32_bf16 v[118:121], v[146:149], v[162:165], v[118:121]
	v_mfma_f32_16x16x32_bf16 v[114:117], v[154:157], v[162:165], v[114:117]
	v_mfma_f32_16x16x32_bf16 v[102:105], v[146:149], v[170:173], v[102:105]
	v_mfma_f32_16x16x32_bf16 v[98:101], v[154:157], v[170:173], v[98:101]
	v_mfma_f32_16x16x32_bf16 v[86:89], v[146:149], v[178:181], v[86:89]
	v_mfma_f32_16x16x32_bf16 v[82:85], v[154:157], v[178:181], v[82:85]
	v_mfma_f32_16x16x32_bf16 v[70:73], v[146:149], v[186:189], v[70:73]
	v_mfma_f32_16x16x32_bf16 v[66:69], v[154:157], v[186:189], v[66:69]
	v_mfma_f32_16x16x32_bf16 v[118:121], v[150:153], v[166:169], v[118:121]
	v_mfma_f32_16x16x32_bf16 v[114:117], v[158:161], v[166:169], v[114:117]
	v_mfma_f32_16x16x32_bf16 v[102:105], v[150:153], v[174:177], v[102:105]
	v_mfma_f32_16x16x32_bf16 v[98:101], v[158:161], v[174:177], v[98:101]
	v_mfma_f32_16x16x32_bf16 v[86:89], v[150:153], v[182:185], v[86:89]
	v_mfma_f32_16x16x32_bf16 v[82:85], v[158:161], v[182:185], v[82:85]
	v_mfma_f32_16x16x32_bf16 v[70:73], v[150:153], v[190:193], v[70:73]
	v_mfma_f32_16x16x32_bf16 v[66:69], v[158:161], v[190:193], v[66:69]
	s_barrier
	s_setprio 0
	s_add_i32 s37, s37, s66
	v_lshl_add_u64 v[212:213], v[212:213], 0, s[10:11]
	s_mov_b32 m0, s37
	ds_read_b128 v[162:165], v234 offset:49152
	ds_read_b128 v[166:169], v234 offset:50176
	ds_read_b128 v[170:173], v234 offset:51200
	ds_read_b128 v[174:177], v234 offset:52224
	ds_read_b128 v[178:181], v234 offset:53248
	ds_read_b128 v[182:185], v234 offset:54272
	ds_read_b128 v[186:189], v234 offset:55296
	ds_read_b128 v[190:193], v234 offset:56320
	global_load_lds_dwordx4 v[212:213], off
	s_add_i32 m0, s37, 0x2000
	s_add_u32 s60, s60, 0x40080
	v_lshl_add_u64 v[212:213], v[214:215], 0, s[10:11]
	s_addc_u32 s61, s61, 0
	s_add_i32 s37, s51, s66
	global_load_lds_dwordx4 v[212:213], off
	v_lshl_add_u64 v[212:213], s[60:61], 0, v[0:1]
	s_mov_b32 m0, s37
	s_nop 0
	global_load_lds_dwordx4 v[212:213], off
	v_lshl_add_u64 v[212:213], s[60:61], 0, v[202:203]
	s_add_i32 m0, s37, 0x2000
	s_nop 0
	global_load_lds_dwordx4 v[212:213], off
	v_lshl_add_u64 v[212:213], v[216:217], 0, s[10:11]
	s_mov_b32 m0, s70
	s_nop 0
	global_load_lds_dwordx4 v[212:213], off
	v_lshl_add_u64 v[212:213], v[218:219], 0, s[10:11]
	s_mov_b32 m0, s71
	s_nop 0
	global_load_lds_dwordx4 v[212:213], off
	s_waitcnt vmcnt(8)
	s_waitcnt lgkmcnt(0)
	s_setprio 1
	s_barrier
	v_mfma_f32_16x16x32_bf16 v[62:65], v[126:129], v[162:165], v[62:65]
	v_mfma_f32_16x16x32_bf16 v[58:61], v[138:141], v[162:165], v[58:61]
	v_mfma_f32_16x16x32_bf16 v[46:49], v[126:129], v[170:173], v[46:49]
	v_mfma_f32_16x16x32_bf16 v[42:45], v[138:141], v[170:173], v[42:45]
	v_mfma_f32_16x16x32_bf16 v[30:33], v[126:129], v[178:181], v[30:33]
	v_mfma_f32_16x16x32_bf16 v[26:29], v[138:141], v[178:181], v[26:29]
	v_mfma_f32_16x16x32_bf16 v[14:17], v[126:129], v[186:189], v[14:17]
	v_mfma_f32_16x16x32_bf16 v[10:13], v[138:141], v[186:189], v[10:13]
	v_mfma_f32_16x16x32_bf16 v[62:65], v[134:137], v[166:169], v[62:65]
	v_mfma_f32_16x16x32_bf16 v[58:61], v[142:145], v[166:169], v[58:61]
	v_mfma_f32_16x16x32_bf16 v[46:49], v[134:137], v[174:177], v[46:49]
	v_mfma_f32_16x16x32_bf16 v[42:45], v[142:145], v[174:177], v[42:45]
	v_mfma_f32_16x16x32_bf16 v[30:33], v[134:137], v[182:185], v[30:33]
	v_mfma_f32_16x16x32_bf16 v[26:29], v[142:145], v[182:185], v[26:29]
	v_mfma_f32_16x16x32_bf16 v[14:17], v[134:137], v[190:193], v[14:17]
	v_mfma_f32_16x16x32_bf16 v[10:13], v[142:145], v[190:193], v[10:13]
	v_mfma_f32_16x16x32_bf16 v[54:57], v[146:149], v[162:165], v[54:57]
	v_mfma_f32_16x16x32_bf16 v[50:53], v[154:157], v[162:165], v[50:53]
	v_mfma_f32_16x16x32_bf16 v[38:41], v[146:149], v[170:173], v[38:41]
	v_mfma_f32_16x16x32_bf16 v[34:37], v[154:157], v[170:173], v[34:37]
	v_mfma_f32_16x16x32_bf16 v[22:25], v[146:149], v[178:181], v[22:25]
	v_mfma_f32_16x16x32_bf16 v[18:21], v[154:157], v[178:181], v[18:21]
	v_mfma_f32_16x16x32_bf16 v[6:9], v[146:149], v[186:189], v[6:9]
	v_mfma_f32_16x16x32_bf16 v[2:5], v[154:157], v[186:189], v[2:5]
	v_mfma_f32_16x16x32_bf16 v[54:57], v[150:153], v[166:169], v[54:57]
	v_mfma_f32_16x16x32_bf16 v[50:53], v[158:161], v[166:169], v[50:53]
	v_mfma_f32_16x16x32_bf16 v[38:41], v[150:153], v[174:177], v[38:41]
	v_mfma_f32_16x16x32_bf16 v[34:37], v[158:161], v[174:177], v[34:37]
	v_mfma_f32_16x16x32_bf16 v[22:25], v[150:153], v[182:185], v[22:25]
	v_mfma_f32_16x16x32_bf16 v[18:21], v[158:161], v[182:185], v[18:21]
	v_mfma_f32_16x16x32_bf16 v[6:9], v[150:153], v[190:193], v[6:9]
	v_mfma_f32_16x16x32_bf16 v[2:5], v[158:161], v[190:193], v[2:5]
	s_barrier
	s_setprio 0
	s_add_i32 s36, s36, 2
	s_add_u32 s29, s29, 0x100
	s_addc_u32 s33, s33, 0
	s_add_u32 s14, s14, 0x100
	s_addc_u32 s15, s15, 0
	s_cmp_gt_u32 s36, 13
	s_cbranch_scc0 .LBB0_731
	s_and_b64 vcc, exec, s[48:49]
	s_cbranch_vccz .LBB0_734
	s_barrier
